# v15 + leading half takes the epilogue-alignment barrier behind its epilogue loads and cvts instead of in front of the epilogue
# baseline (speedup 1.0000x reference)
.Lsp_p2:
.LBB0_213:
	ds_read_b128 v[146:149], v156
	ds_read_b128 v[150:153], v156 offset:1024
	ds_read_b128 v[160:163], v156 offset:2048
	ds_read_b128 v[164:167], v156 offset:3072
	ds_read_b128 v[168:171], v157
	ds_read_b128 v[172:175], v157 offset:1024
	ds_read_b128 v[176:179], v157 offset:2048
	ds_read_b128 v[180:183], v157 offset:3072
	s_add_u32 s19, s84, 0xfff80080
	s_addc_u32 s20, s85, -1
	s_cmp_eq_u32 s18, 28
	s_cselect_b32 s89, s8, s20
	s_cselect_b32 s88, s9, s19
	s_cselect_b32 s87, s12, s17
	s_cselect_b32 s86, s13, s16
	v_lshl_add_u64 v[216:217], s[84:85], 0, v[138:139]
	s_add_i32 m0, s57, 0xc000
	ds_read_b128 v[184:187], v158
	ds_read_b128 v[188:191], v158 offset:1024
	ds_read_b128 v[192:195], v158 offset:2048
	ds_read_b128 v[196:199], v158 offset:3072
	ds_read_b128 v[200:203], v158 offset:4096
	ds_read_b128 v[204:207], v158 offset:5120
	ds_read_b128 v[208:211], v158 offset:6144
	ds_read_b128 v[212:215], v158 offset:7168
	global_load_lds_dwordx4 v[216:217], off
	v_lshl_add_u64 v[216:217], s[84:85], 0, v[140:141]
	s_add_i32 m0, s57, 0xe000
	s_nop 0
	global_load_lds_dwordx4 v[216:217], off
	s_waitcnt vmcnt(8)
	s_waitcnt lgkmcnt(0)
	s_barrier
	s_waitcnt lgkmcnt(0)
	v_mfma_i32_16x16x64_i8 v[126:129], v[146:149], v[184:187], v[126:129]
	v_mfma_i32_16x16x64_i8 v[122:125], v[160:163], v[184:187], v[122:125]
	v_mfma_i32_16x16x64_i8 v[110:113], v[146:149], v[192:195], v[110:113]
	v_mfma_i32_16x16x64_i8 v[106:109], v[160:163], v[192:195], v[106:109]
	v_mfma_i32_16x16x64_i8 v[94:97], v[146:149], v[200:203], v[94:97]
	v_mfma_i32_16x16x64_i8 v[90:93], v[160:163], v[200:203], v[90:93]
	v_mfma_i32_16x16x64_i8 v[78:81], v[146:149], v[208:211], v[78:81]
	v_mfma_i32_16x16x64_i8 v[74:77], v[160:163], v[208:211], v[74:77]
	v_mfma_i32_16x16x64_i8 v[126:129], v[150:153], v[188:191], v[126:129]
	v_mfma_i32_16x16x64_i8 v[122:125], v[164:167], v[188:191], v[122:125]
	v_mfma_i32_16x16x64_i8 v[110:113], v[150:153], v[196:199], v[110:113]
	v_mfma_i32_16x16x64_i8 v[106:109], v[164:167], v[196:199], v[106:109]
	v_mfma_i32_16x16x64_i8 v[94:97], v[150:153], v[204:207], v[94:97]
	v_mfma_i32_16x16x64_i8 v[90:93], v[164:167], v[204:207], v[90:93]
	v_mfma_i32_16x16x64_i8 v[78:81], v[150:153], v[212:215], v[78:81]
	v_mfma_i32_16x16x64_i8 v[74:77], v[164:167], v[212:215], v[74:77]
	v_mfma_i32_16x16x64_i8 v[118:121], v[168:171], v[184:187], v[118:121]
	v_mfma_i32_16x16x64_i8 v[114:117], v[176:179], v[184:187], v[114:117]
	v_mfma_i32_16x16x64_i8 v[102:105], v[168:171], v[192:195], v[102:105]
	v_mfma_i32_16x16x64_i8 v[98:101], v[176:179], v[192:195], v[98:101]
	v_mfma_i32_16x16x64_i8 v[86:89], v[168:171], v[200:203], v[86:89]
	v_mfma_i32_16x16x64_i8 v[82:85], v[176:179], v[200:203], v[82:85]
	v_mfma_i32_16x16x64_i8 v[70:73], v[168:171], v[208:211], v[70:73]
	v_mfma_i32_16x16x64_i8 v[66:69], v[176:179], v[208:211], v[66:69]
	v_mfma_i32_16x16x64_i8 v[118:121], v[172:175], v[188:191], v[118:121]
	v_mfma_i32_16x16x64_i8 v[114:117], v[180:183], v[188:191], v[114:117]
	v_mfma_i32_16x16x64_i8 v[102:105], v[172:175], v[196:199], v[102:105]
	v_mfma_i32_16x16x64_i8 v[98:101], v[180:183], v[196:199], v[98:101]
	v_mfma_i32_16x16x64_i8 v[86:89], v[172:175], v[204:207], v[86:89]
	v_mfma_i32_16x16x64_i8 v[82:85], v[180:183], v[204:207], v[82:85]
	v_mfma_i32_16x16x64_i8 v[70:73], v[172:175], v[212:215], v[70:73]
	v_mfma_i32_16x16x64_i8 v[66:69], v[180:183], v[212:215], v[66:69]
	s_barrier
	s_add_i32 s19, s83, s35
	v_lshl_add_u64 v[216:217], s[86:87], 0, v[134:135]
	s_mov_b32 m0, s19
	ds_read_b128 v[184:187], v158 offset:16384
	ds_read_b128 v[188:191], v158 offset:17408
	ds_read_b128 v[192:195], v158 offset:18432
	ds_read_b128 v[196:199], v158 offset:19456
	ds_read_b128 v[200:203], v158 offset:20480
	ds_read_b128 v[204:207], v158 offset:21504
	ds_read_b128 v[208:211], v158 offset:22528
	ds_read_b128 v[212:215], v158 offset:23552
	global_load_lds_dwordx4 v[216:217], off
	s_add_i32 m0, s19, 0x2000
	s_add_u32 s20, s86, 0x80000
	v_lshl_add_u64 v[218:219], s[86:87], 0, v[130:131]
	s_addc_u32 s21, s87, 0
	s_add_i32 s19, s90, s35
	global_load_lds_dwordx4 v[218:219], off
	v_lshl_add_u64 v[220:221], s[20:21], 0, v[134:135]
	s_mov_b32 m0, s19
	v_lshl_add_u64 v[222:223], s[88:89], 0, v[132:133]
	global_load_lds_dwordx4 v[220:221], off
	v_lshl_add_u64 v[220:221], s[20:21], 0, v[130:131]
	s_add_i32 m0, s19, 0x2000
	s_nop 0
	global_load_lds_dwordx4 v[220:221], off
	v_lshl_add_u64 v[220:221], s[88:89], 0, v[136:137]
	s_mov_b32 m0, s57
	s_nop 0
	global_load_lds_dwordx4 v[220:221], off
	s_mov_b32 m0, s58
	s_nop 0
	global_load_lds_dwordx4 v[222:223], off
	s_waitcnt vmcnt(8)
	s_waitcnt lgkmcnt(0)
	s_barrier
	s_waitcnt lgkmcnt(0)
	v_mfma_i32_16x16x64_i8 v[62:65], v[146:149], v[184:187], v[62:65]
	v_mfma_i32_16x16x64_i8 v[58:61], v[160:163], v[184:187], v[58:61]
	v_mfma_i32_16x16x64_i8 v[46:49], v[146:149], v[192:195], v[46:49]
	v_mfma_i32_16x16x64_i8 v[42:45], v[160:163], v[192:195], v[42:45]
	v_mfma_i32_16x16x64_i8 v[30:33], v[146:149], v[200:203], v[30:33]
	v_mfma_i32_16x16x64_i8 v[26:29], v[160:163], v[200:203], v[26:29]
	v_mfma_i32_16x16x64_i8 v[14:17], v[146:149], v[208:211], v[14:17]
	v_mfma_i32_16x16x64_i8 v[10:13], v[160:163], v[208:211], v[10:13]
	v_mfma_i32_16x16x64_i8 v[62:65], v[150:153], v[188:191], v[62:65]
	v_mfma_i32_16x16x64_i8 v[58:61], v[164:167], v[188:191], v[58:61]
	v_mfma_i32_16x16x64_i8 v[46:49], v[150:153], v[196:199], v[46:49]
	v_mfma_i32_16x16x64_i8 v[42:45], v[164:167], v[196:199], v[42:45]
	v_mfma_i32_16x16x64_i8 v[30:33], v[150:153], v[204:207], v[30:33]
	v_mfma_i32_16x16x64_i8 v[26:29], v[164:167], v[204:207], v[26:29]
	v_mfma_i32_16x16x64_i8 v[14:17], v[150:153], v[212:215], v[14:17]
	v_mfma_i32_16x16x64_i8 v[10:13], v[164:167], v[212:215], v[10:13]
	v_mfma_i32_16x16x64_i8 v[54:57], v[168:171], v[184:187], v[54:57]
	v_mfma_i32_16x16x64_i8 v[50:53], v[176:179], v[184:187], v[50:53]
	v_mfma_i32_16x16x64_i8 v[38:41], v[168:171], v[192:195], v[38:41]
	v_mfma_i32_16x16x64_i8 v[34:37], v[176:179], v[192:195], v[34:37]
	v_mfma_i32_16x16x64_i8 v[22:25], v[168:171], v[200:203], v[22:25]
	v_mfma_i32_16x16x64_i8 v[18:21], v[176:179], v[200:203], v[18:21]
	v_mfma_i32_16x16x64_i8 v[6:9], v[168:171], v[208:211], v[6:9]
	v_mfma_i32_16x16x64_i8 v[2:5], v[176:179], v[208:211], v[2:5]
	v_mfma_i32_16x16x64_i8 v[54:57], v[172:175], v[188:191], v[54:57]
	v_mfma_i32_16x16x64_i8 v[50:53], v[180:183], v[188:191], v[50:53]
	v_mfma_i32_16x16x64_i8 v[38:41], v[172:175], v[196:199], v[38:41]
	v_mfma_i32_16x16x64_i8 v[34:37], v[180:183], v[196:199], v[34:37]
	v_mfma_i32_16x16x64_i8 v[22:25], v[172:175], v[204:207], v[22:25]
	v_mfma_i32_16x16x64_i8 v[18:21], v[180:183], v[204:207], v[18:21]
	v_mfma_i32_16x16x64_i8 v[6:9], v[172:175], v[212:215], v[6:9]
	v_mfma_i32_16x16x64_i8 v[2:5], v[180:183], v[212:215], v[2:5]
	s_barrier
	s_add_i32 s19, 0, 0x18000
	v_add_u32_e32 v159, s19, v154
	s_add_i32 s22, 0, 0x1c000
	ds_read_b128 v[146:149], v159
	ds_read_b128 v[150:153], v159 offset:1024
	ds_read_b128 v[160:163], v159 offset:2048
	ds_read_b128 v[164:167], v159 offset:3072
	v_add_u32_e32 v159, s22, v154
	ds_read_b128 v[168:171], v159
	ds_read_b128 v[172:175], v159 offset:1024
	ds_read_b128 v[176:179], v159 offset:2048
	ds_read_b128 v[180:183], v159 offset:3072
	s_add_u32 s20, s88, 0x80000
	s_addc_u32 s21, s89, 0
	s_mov_b32 m0, s59
	v_lshl_add_u64 v[224:225], s[20:21], 0, v[136:137]
	ds_read_b128 v[184:187], v158 offset:32768
	ds_read_b128 v[188:191], v158 offset:33792
	ds_read_b128 v[192:195], v158 offset:34816
	ds_read_b128 v[196:199], v158 offset:35840
	ds_read_b128 v[200:203], v158 offset:36864
	ds_read_b128 v[204:207], v158 offset:37888
	ds_read_b128 v[208:211], v158 offset:38912
	ds_read_b128 v[212:215], v158 offset:39936
	global_load_lds_dwordx4 v[224:225], off
	v_lshl_add_u64 v[224:225], s[20:21], 0, v[132:133]
	s_mov_b32 m0, s61
	s_nop 0
	global_load_lds_dwordx4 v[224:225], off
	s_waitcnt vmcnt(8)
	s_waitcnt lgkmcnt(0)
	s_barrier
	s_waitcnt lgkmcnt(0)
	v_mfma_i32_16x16x64_i8 v[126:129], v[146:149], v[184:187], v[126:129]
	v_mfma_i32_16x16x64_i8 v[122:125], v[160:163], v[184:187], v[122:125]
	v_mfma_i32_16x16x64_i8 v[110:113], v[146:149], v[192:195], v[110:113]
	v_mfma_i32_16x16x64_i8 v[106:109], v[160:163], v[192:195], v[106:109]
	v_mfma_i32_16x16x64_i8 v[94:97], v[146:149], v[200:203], v[94:97]
	v_mfma_i32_16x16x64_i8 v[90:93], v[160:163], v[200:203], v[90:93]
	v_mfma_i32_16x16x64_i8 v[78:81], v[146:149], v[208:211], v[78:81]
	v_mfma_i32_16x16x64_i8 v[74:77], v[160:163], v[208:211], v[74:77]
	v_mfma_i32_16x16x64_i8 v[126:129], v[150:153], v[188:191], v[126:129]
	v_mfma_i32_16x16x64_i8 v[122:125], v[164:167], v[188:191], v[122:125]
	v_mfma_i32_16x16x64_i8 v[110:113], v[150:153], v[196:199], v[110:113]
	v_mfma_i32_16x16x64_i8 v[106:109], v[164:167], v[196:199], v[106:109]
	v_mfma_i32_16x16x64_i8 v[94:97], v[150:153], v[204:207], v[94:97]
	v_mfma_i32_16x16x64_i8 v[90:93], v[164:167], v[204:207], v[90:93]
	v_mfma_i32_16x16x64_i8 v[78:81], v[150:153], v[212:215], v[78:81]
	v_mfma_i32_16x16x64_i8 v[74:77], v[164:167], v[212:215], v[74:77]
	v_mfma_i32_16x16x64_i8 v[118:121], v[168:171], v[184:187], v[118:121]
	v_mfma_i32_16x16x64_i8 v[114:117], v[176:179], v[184:187], v[114:117]
	v_mfma_i32_16x16x64_i8 v[102:105], v[168:171], v[192:195], v[102:105]
	v_mfma_i32_16x16x64_i8 v[98:101], v[176:179], v[192:195], v[98:101]
	v_mfma_i32_16x16x64_i8 v[86:89], v[168:171], v[200:203], v[86:89]
	v_mfma_i32_16x16x64_i8 v[82:85], v[176:179], v[200:203], v[82:85]
	v_mfma_i32_16x16x64_i8 v[70:73], v[168:171], v[208:211], v[70:73]
	v_mfma_i32_16x16x64_i8 v[66:69], v[176:179], v[208:211], v[66:69]
	v_mfma_i32_16x16x64_i8 v[118:121], v[172:175], v[188:191], v[118:121]
	v_mfma_i32_16x16x64_i8 v[114:117], v[180:183], v[188:191], v[114:117]
	v_mfma_i32_16x16x64_i8 v[102:105], v[172:175], v[196:199], v[102:105]
	v_mfma_i32_16x16x64_i8 v[98:101], v[180:183], v[196:199], v[98:101]
	v_mfma_i32_16x16x64_i8 v[86:89], v[172:175], v[204:207], v[86:89]
	v_mfma_i32_16x16x64_i8 v[82:85], v[180:183], v[204:207], v[82:85]
	v_mfma_i32_16x16x64_i8 v[70:73], v[172:175], v[212:215], v[70:73]
	v_mfma_i32_16x16x64_i8 v[66:69], v[180:183], v[212:215], v[66:69]
	s_barrier
	s_add_i32 s19, s19, s35
	v_lshl_add_u64 v[216:217], v[216:217], 0, s[4:5]
	s_mov_b32 m0, s19
	ds_read_b128 v[184:187], v158 offset:49152
	ds_read_b128 v[188:191], v158 offset:50176
	ds_read_b128 v[192:195], v158 offset:51200
	ds_read_b128 v[196:199], v158 offset:52224
	ds_read_b128 v[200:203], v158 offset:53248
	ds_read_b128 v[204:207], v158 offset:54272
	ds_read_b128 v[208:211], v158 offset:55296
	ds_read_b128 v[212:215], v158 offset:56320
	global_load_lds_dwordx4 v[216:217], off
	s_add_i32 m0, s19, 0x2000
	s_add_u32 s20, s86, 0x80080
	v_lshl_add_u64 v[216:217], v[218:219], 0, s[4:5]
	s_addc_u32 s21, s87, 0
	s_add_i32 s19, s22, s35
	global_load_lds_dwordx4 v[216:217], off
	v_lshl_add_u64 v[216:217], s[20:21], 0, v[134:135]
	s_mov_b32 m0, s19
	s_nop 0
	global_load_lds_dwordx4 v[216:217], off
	v_lshl_add_u64 v[216:217], s[20:21], 0, v[130:131]
	s_add_i32 m0, s19, 0x2000
	s_nop 0
	global_load_lds_dwordx4 v[216:217], off
	v_lshl_add_u64 v[216:217], v[220:221], 0, s[4:5]
	s_mov_b32 m0, s67
	s_nop 0
	global_load_lds_dwordx4 v[216:217], off
	v_lshl_add_u64 v[216:217], v[222:223], 0, s[4:5]
	s_mov_b32 m0, s68
	s_nop 0
	global_load_lds_dwordx4 v[216:217], off
	s_waitcnt vmcnt(8)
	s_waitcnt lgkmcnt(0)
	s_barrier
	s_waitcnt lgkmcnt(0)
	v_mfma_i32_16x16x64_i8 v[62:65], v[146:149], v[184:187], v[62:65]
	v_mfma_i32_16x16x64_i8 v[58:61], v[160:163], v[184:187], v[58:61]
	v_mfma_i32_16x16x64_i8 v[46:49], v[146:149], v[192:195], v[46:49]
	v_mfma_i32_16x16x64_i8 v[42:45], v[160:163], v[192:195], v[42:45]
	v_mfma_i32_16x16x64_i8 v[30:33], v[146:149], v[200:203], v[30:33]
	v_mfma_i32_16x16x64_i8 v[26:29], v[160:163], v[200:203], v[26:29]
	v_mfma_i32_16x16x64_i8 v[14:17], v[146:149], v[208:211], v[14:17]
	v_mfma_i32_16x16x64_i8 v[10:13], v[160:163], v[208:211], v[10:13]
	v_mfma_i32_16x16x64_i8 v[62:65], v[150:153], v[188:191], v[62:65]
	v_mfma_i32_16x16x64_i8 v[58:61], v[164:167], v[188:191], v[58:61]
	v_mfma_i32_16x16x64_i8 v[46:49], v[150:153], v[196:199], v[46:49]
	v_mfma_i32_16x16x64_i8 v[42:45], v[164:167], v[196:199], v[42:45]
	v_mfma_i32_16x16x64_i8 v[30:33], v[150:153], v[204:207], v[30:33]
	v_mfma_i32_16x16x64_i8 v[26:29], v[164:167], v[204:207], v[26:29]
	v_mfma_i32_16x16x64_i8 v[14:17], v[150:153], v[212:215], v[14:17]
	v_mfma_i32_16x16x64_i8 v[10:13], v[164:167], v[212:215], v[10:13]
	v_mfma_i32_16x16x64_i8 v[54:57], v[168:171], v[184:187], v[54:57]
	v_mfma_i32_16x16x64_i8 v[50:53], v[176:179], v[184:187], v[50:53]
	v_mfma_i32_16x16x64_i8 v[38:41], v[168:171], v[192:195], v[38:41]
	v_mfma_i32_16x16x64_i8 v[34:37], v[176:179], v[192:195], v[34:37]
	v_mfma_i32_16x16x64_i8 v[22:25], v[168:171], v[200:203], v[22:25]
	v_mfma_i32_16x16x64_i8 v[18:21], v[176:179], v[200:203], v[18:21]
	v_mfma_i32_16x16x64_i8 v[6:9], v[168:171], v[208:211], v[6:9]
	v_mfma_i32_16x16x64_i8 v[2:5], v[176:179], v[208:211], v[2:5]
	v_mfma_i32_16x16x64_i8 v[54:57], v[172:175], v[188:191], v[54:57]
	v_mfma_i32_16x16x64_i8 v[50:53], v[180:183], v[188:191], v[50:53]
	v_mfma_i32_16x16x64_i8 v[38:41], v[172:175], v[196:199], v[38:41]
	v_mfma_i32_16x16x64_i8 v[34:37], v[180:183], v[196:199], v[34:37]
	v_mfma_i32_16x16x64_i8 v[22:25], v[172:175], v[204:207], v[22:25]
	v_mfma_i32_16x16x64_i8 v[18:21], v[180:183], v[204:207], v[18:21]
	v_mfma_i32_16x16x64_i8 v[6:9], v[172:175], v[212:215], v[6:9]
	v_mfma_i32_16x16x64_i8 v[2:5], v[180:183], v[212:215], v[2:5]
	s_barrier
	s_add_i32 s18, s18, 2
	s_add_u32 s84, s84, 0x100
	s_addc_u32 s85, s85, 0
	s_add_u32 s16, s16, 0x100
	s_addc_u32 s17, s17, 0
	s_cmp_gt_u32 s18, 29
	s_cbranch_scc0 .LBB0_213
	s_setprio 0
	s_and_b64 vcc, exec, s[6:7]
	s_cbranch_vccz .LBB0_216

.Lsp_p3:
.LBB0_362:
	ds_read_b128 v[106:109], v168
	ds_read_b128 v[110:113], v168 offset:1024
	ds_read_b128 v[114:117], v168 offset:2048
	ds_read_b128 v[122:125], v168 offset:3072
	ds_read_b128 v[160:163], v169
	ds_read_b128 v[172:175], v169 offset:1024
	ds_read_b128 v[176:179], v169 offset:2048
	ds_read_b128 v[180:183], v169 offset:3072
	s_add_u32 s16, s6, 0xffea8080
	s_addc_u32 s17, s7, -1
	s_cmpk_eq_i32 s13, 0x52
	s_cselect_b32 s85, s51, s17
	s_cselect_b32 s84, s50, s16
	s_cselect_b32 s83, s81, s12
	s_cselect_b32 s82, s80, s8
	v_lshl_add_u64 v[216:217], s[6:7], 0, v[154:155]
	s_add_i32 m0, s56, 0xc000
	ds_read_b128 v[184:187], v170
	ds_read_b128 v[188:191], v170 offset:1024
	ds_read_b128 v[192:195], v170 offset:2048
	ds_read_b128 v[196:199], v170 offset:3072
	ds_read_b128 v[200:203], v170 offset:4096
	ds_read_b128 v[204:207], v170 offset:5120
	ds_read_b128 v[208:211], v170 offset:6144
	ds_read_b128 v[212:215], v170 offset:7168
	global_load_lds_dwordx4 v[216:217], off
	v_lshl_add_u64 v[216:217], s[6:7], 0, v[156:157]
	s_add_i32 m0, s56, 0xe000
	s_nop 0
	global_load_lds_dwordx4 v[216:217], off
	s_waitcnt vmcnt(8)
	s_waitcnt lgkmcnt(0)
	s_barrier
	s_waitcnt lgkmcnt(0)
	v_mfma_i32_16x16x64_i8 v[142:145], v[106:109], v[184:187], v[142:145]
	v_mfma_i32_16x16x64_i8 v[138:141], v[114:117], v[184:187], v[138:141]
	v_mfma_i32_16x16x64_i8 v[126:129], v[106:109], v[192:195], v[126:129]
	v_mfma_i32_16x16x64_i8 v[118:121], v[114:117], v[192:195], v[118:121]
	v_mfma_i32_16x16x64_i8 v[94:97], v[106:109], v[200:203], v[94:97]
	v_mfma_i32_16x16x64_i8 v[90:93], v[114:117], v[200:203], v[90:93]
	v_mfma_i32_16x16x64_i8 v[78:81], v[106:109], v[208:211], v[78:81]
	v_mfma_i32_16x16x64_i8 v[74:77], v[114:117], v[208:211], v[74:77]
	v_mfma_i32_16x16x64_i8 v[142:145], v[110:113], v[188:191], v[142:145]
	v_mfma_i32_16x16x64_i8 v[138:141], v[122:125], v[188:191], v[138:141]
	v_mfma_i32_16x16x64_i8 v[126:129], v[110:113], v[196:199], v[126:129]
	v_mfma_i32_16x16x64_i8 v[118:121], v[122:125], v[196:199], v[118:121]
	v_mfma_i32_16x16x64_i8 v[94:97], v[110:113], v[204:207], v[94:97]
	v_mfma_i32_16x16x64_i8 v[90:93], v[122:125], v[204:207], v[90:93]
	v_mfma_i32_16x16x64_i8 v[78:81], v[110:113], v[212:215], v[78:81]
	v_mfma_i32_16x16x64_i8 v[74:77], v[122:125], v[212:215], v[74:77]
	v_mfma_i32_16x16x64_i8 v[134:137], v[160:163], v[184:187], v[134:137]
	v_mfma_i32_16x16x64_i8 v[130:133], v[176:179], v[184:187], v[130:133]
	v_mfma_i32_16x16x64_i8 v[102:105], v[160:163], v[192:195], v[102:105]
	v_mfma_i32_16x16x64_i8 v[98:101], v[176:179], v[192:195], v[98:101]
	v_mfma_i32_16x16x64_i8 v[86:89], v[160:163], v[200:203], v[86:89]
	v_mfma_i32_16x16x64_i8 v[82:85], v[176:179], v[200:203], v[82:85]
	v_mfma_i32_16x16x64_i8 v[70:73], v[160:163], v[208:211], v[70:73]
	v_mfma_i32_16x16x64_i8 v[66:69], v[176:179], v[208:211], v[66:69]
	v_mfma_i32_16x16x64_i8 v[134:137], v[172:175], v[188:191], v[134:137]
	v_mfma_i32_16x16x64_i8 v[130:133], v[180:183], v[188:191], v[130:133]
	v_mfma_i32_16x16x64_i8 v[102:105], v[172:175], v[196:199], v[102:105]
	v_mfma_i32_16x16x64_i8 v[98:101], v[180:183], v[196:199], v[98:101]
	v_mfma_i32_16x16x64_i8 v[86:89], v[172:175], v[204:207], v[86:89]
	v_mfma_i32_16x16x64_i8 v[82:85], v[180:183], v[204:207], v[82:85]
	v_mfma_i32_16x16x64_i8 v[70:73], v[172:175], v[212:215], v[70:73]
	v_mfma_i32_16x16x64_i8 v[66:69], v[180:183], v[212:215], v[66:69]
	s_barrier
	s_add_i32 s16, s87, s35
	v_lshl_add_u64 v[216:217], s[82:83], 0, v[148:149]
	s_mov_b32 m0, s16
	ds_read_b128 v[184:187], v170 offset:16384
	ds_read_b128 v[188:191], v170 offset:17408
	ds_read_b128 v[192:195], v170 offset:18432
	ds_read_b128 v[196:199], v170 offset:19456
	ds_read_b128 v[200:203], v170 offset:20480
	ds_read_b128 v[204:207], v170 offset:21504
	ds_read_b128 v[208:211], v170 offset:22528
	ds_read_b128 v[212:215], v170 offset:23552
	global_load_lds_dwordx4 v[216:217], off
	s_add_i32 m0, s16, 0x2000
	s_add_u32 s16, s82, 0x158000
	v_lshl_add_u64 v[218:219], s[82:83], 0, v[152:153]
	s_addc_u32 s17, s83, 0
	s_add_i32 s18, s88, s35
	global_load_lds_dwordx4 v[218:219], off
	v_lshl_add_u64 v[220:221], s[16:17], 0, v[148:149]
	s_mov_b32 m0, s18
	v_lshl_add_u64 v[222:223], s[84:85], 0, v[150:151]
	global_load_lds_dwordx4 v[220:221], off
	v_lshl_add_u64 v[220:221], s[16:17], 0, v[152:153]
	s_add_i32 m0, s18, 0x2000
	s_nop 0
	global_load_lds_dwordx4 v[220:221], off
	v_lshl_add_u64 v[220:221], s[84:85], 0, v[146:147]
	s_mov_b32 m0, s56
	s_nop 0
	global_load_lds_dwordx4 v[220:221], off
	s_mov_b32 m0, s57
	s_nop 0
	global_load_lds_dwordx4 v[222:223], off
	s_waitcnt vmcnt(8)
	s_waitcnt lgkmcnt(0)
	s_barrier
	s_waitcnt lgkmcnt(0)
	v_mfma_i32_16x16x64_i8 v[62:65], v[106:109], v[184:187], v[62:65]
	v_mfma_i32_16x16x64_i8 v[58:61], v[114:117], v[184:187], v[58:61]
	v_mfma_i32_16x16x64_i8 v[46:49], v[106:109], v[192:195], v[46:49]
	v_mfma_i32_16x16x64_i8 v[42:45], v[114:117], v[192:195], v[42:45]
	v_mfma_i32_16x16x64_i8 v[30:33], v[106:109], v[200:203], v[30:33]
	v_mfma_i32_16x16x64_i8 v[26:29], v[114:117], v[200:203], v[26:29]
	v_mfma_i32_16x16x64_i8 v[14:17], v[106:109], v[208:211], v[14:17]
	v_mfma_i32_16x16x64_i8 v[10:13], v[114:117], v[208:211], v[10:13]
	v_mfma_i32_16x16x64_i8 v[62:65], v[110:113], v[188:191], v[62:65]
	v_mfma_i32_16x16x64_i8 v[58:61], v[122:125], v[188:191], v[58:61]
	v_mfma_i32_16x16x64_i8 v[46:49], v[110:113], v[196:199], v[46:49]
	v_mfma_i32_16x16x64_i8 v[42:45], v[122:125], v[196:199], v[42:45]
	v_mfma_i32_16x16x64_i8 v[30:33], v[110:113], v[204:207], v[30:33]
	v_mfma_i32_16x16x64_i8 v[26:29], v[122:125], v[204:207], v[26:29]
	v_mfma_i32_16x16x64_i8 v[14:17], v[110:113], v[212:215], v[14:17]
	v_mfma_i32_16x16x64_i8 v[10:13], v[122:125], v[212:215], v[10:13]
	v_mfma_i32_16x16x64_i8 v[54:57], v[160:163], v[184:187], v[54:57]
	v_mfma_i32_16x16x64_i8 v[50:53], v[176:179], v[184:187], v[50:53]
	v_mfma_i32_16x16x64_i8 v[38:41], v[160:163], v[192:195], v[38:41]
	v_mfma_i32_16x16x64_i8 v[34:37], v[176:179], v[192:195], v[34:37]
	v_mfma_i32_16x16x64_i8 v[22:25], v[160:163], v[200:203], v[22:25]
	v_mfma_i32_16x16x64_i8 v[18:21], v[176:179], v[200:203], v[18:21]
	v_mfma_i32_16x16x64_i8 v[6:9], v[160:163], v[208:211], v[6:9]
	v_mfma_i32_16x16x64_i8 v[2:5], v[176:179], v[208:211], v[2:5]
	v_mfma_i32_16x16x64_i8 v[54:57], v[172:175], v[188:191], v[54:57]
	v_mfma_i32_16x16x64_i8 v[50:53], v[180:183], v[188:191], v[50:53]
	v_mfma_i32_16x16x64_i8 v[38:41], v[172:175], v[196:199], v[38:41]
	v_mfma_i32_16x16x64_i8 v[34:37], v[180:183], v[196:199], v[34:37]
	v_mfma_i32_16x16x64_i8 v[22:25], v[172:175], v[204:207], v[22:25]
	v_mfma_i32_16x16x64_i8 v[18:21], v[180:183], v[204:207], v[18:21]
	v_mfma_i32_16x16x64_i8 v[6:9], v[172:175], v[212:215], v[6:9]
	v_mfma_i32_16x16x64_i8 v[2:5], v[180:183], v[212:215], v[2:5]
	s_barrier
	s_add_i32 s18, 0, 0x18000
	s_add_i32 s19, 0, 0x1c000
	v_add_u32_e32 v122, s18, v165
	v_add_u32_e32 v164, s19, v165
	ds_read_b128 v[106:109], v122
	ds_read_b128 v[110:113], v122 offset:1024
	ds_read_b128 v[114:117], v122 offset:2048
	ds_read_b128 v[122:125], v122 offset:3072
	ds_read_b128 v[160:163], v164
	ds_read_b128 v[172:175], v164 offset:1024
	ds_read_b128 v[176:179], v164 offset:2048
	ds_read_b128 v[180:183], v164 offset:3072
	s_add_u32 s16, s84, 0x158000
	s_addc_u32 s17, s85, 0
	s_mov_b32 m0, s58
	v_lshl_add_u64 v[224:225], s[16:17], 0, v[146:147]
	ds_read_b128 v[184:187], v170 offset:32768
	ds_read_b128 v[188:191], v170 offset:33792
	ds_read_b128 v[192:195], v170 offset:34816
	ds_read_b128 v[196:199], v170 offset:35840
	ds_read_b128 v[200:203], v170 offset:36864
	ds_read_b128 v[204:207], v170 offset:37888
	ds_read_b128 v[208:211], v170 offset:38912
	ds_read_b128 v[212:215], v170 offset:39936
	global_load_lds_dwordx4 v[224:225], off
	v_lshl_add_u64 v[224:225], s[16:17], 0, v[150:151]
	s_mov_b32 m0, s59
	s_nop 0
	global_load_lds_dwordx4 v[224:225], off
	s_waitcnt vmcnt(8)
	s_waitcnt lgkmcnt(0)
	s_barrier
	s_waitcnt lgkmcnt(0)
	v_mfma_i32_16x16x64_i8 v[142:145], v[106:109], v[184:187], v[142:145]
	v_mfma_i32_16x16x64_i8 v[138:141], v[114:117], v[184:187], v[138:141]
	v_mfma_i32_16x16x64_i8 v[126:129], v[106:109], v[192:195], v[126:129]
	v_mfma_i32_16x16x64_i8 v[118:121], v[114:117], v[192:195], v[118:121]
	v_mfma_i32_16x16x64_i8 v[94:97], v[106:109], v[200:203], v[94:97]
	v_mfma_i32_16x16x64_i8 v[90:93], v[114:117], v[200:203], v[90:93]
	v_mfma_i32_16x16x64_i8 v[78:81], v[106:109], v[208:211], v[78:81]
	v_mfma_i32_16x16x64_i8 v[74:77], v[114:117], v[208:211], v[74:77]
	v_mfma_i32_16x16x64_i8 v[142:145], v[110:113], v[188:191], v[142:145]
	v_mfma_i32_16x16x64_i8 v[138:141], v[122:125], v[188:191], v[138:141]
	v_mfma_i32_16x16x64_i8 v[126:129], v[110:113], v[196:199], v[126:129]
	v_mfma_i32_16x16x64_i8 v[118:121], v[122:125], v[196:199], v[118:121]
	v_mfma_i32_16x16x64_i8 v[94:97], v[110:113], v[204:207], v[94:97]
	v_mfma_i32_16x16x64_i8 v[90:93], v[122:125], v[204:207], v[90:93]
	v_mfma_i32_16x16x64_i8 v[78:81], v[110:113], v[212:215], v[78:81]
	v_mfma_i32_16x16x64_i8 v[74:77], v[122:125], v[212:215], v[74:77]
	v_mfma_i32_16x16x64_i8 v[134:137], v[160:163], v[184:187], v[134:137]
	v_mfma_i32_16x16x64_i8 v[130:133], v[176:179], v[184:187], v[130:133]
	v_mfma_i32_16x16x64_i8 v[102:105], v[160:163], v[192:195], v[102:105]
	v_mfma_i32_16x16x64_i8 v[98:101], v[176:179], v[192:195], v[98:101]
	v_mfma_i32_16x16x64_i8 v[86:89], v[160:163], v[200:203], v[86:89]
	v_mfma_i32_16x16x64_i8 v[82:85], v[176:179], v[200:203], v[82:85]
	v_mfma_i32_16x16x64_i8 v[70:73], v[160:163], v[208:211], v[70:73]
	v_mfma_i32_16x16x64_i8 v[66:69], v[176:179], v[208:211], v[66:69]
	v_mfma_i32_16x16x64_i8 v[134:137], v[172:175], v[188:191], v[134:137]
	v_mfma_i32_16x16x64_i8 v[130:133], v[180:183], v[188:191], v[130:133]
	v_mfma_i32_16x16x64_i8 v[102:105], v[172:175], v[196:199], v[102:105]
	v_mfma_i32_16x16x64_i8 v[98:101], v[180:183], v[196:199], v[98:101]
	v_mfma_i32_16x16x64_i8 v[86:89], v[172:175], v[204:207], v[86:89]
	v_mfma_i32_16x16x64_i8 v[82:85], v[180:183], v[204:207], v[82:85]
	v_mfma_i32_16x16x64_i8 v[70:73], v[172:175], v[212:215], v[70:73]
	v_mfma_i32_16x16x64_i8 v[66:69], v[180:183], v[212:215], v[66:69]
	s_barrier
	s_add_i32 s16, s18, s35
	v_lshl_add_u64 v[216:217], v[216:217], 0, s[44:45]
	s_mov_b32 m0, s16
	ds_read_b128 v[184:187], v170 offset:49152
	ds_read_b128 v[188:191], v170 offset:50176
	ds_read_b128 v[192:195], v170 offset:51200
	ds_read_b128 v[196:199], v170 offset:52224
	ds_read_b128 v[200:203], v170 offset:53248
	ds_read_b128 v[204:207], v170 offset:54272
	ds_read_b128 v[208:211], v170 offset:55296
	ds_read_b128 v[212:215], v170 offset:56320
	global_load_lds_dwordx4 v[216:217], off
	s_add_i32 m0, s16, 0x2000
	s_add_u32 s16, s82, 0x158080
	v_lshl_add_u64 v[216:217], v[218:219], 0, s[44:45]
	s_addc_u32 s17, s83, 0
	s_add_i32 s18, s19, s35
	global_load_lds_dwordx4 v[216:217], off
	v_lshl_add_u64 v[216:217], s[16:17], 0, v[148:149]
	s_mov_b32 m0, s18
	s_nop 0
	global_load_lds_dwordx4 v[216:217], off
	v_lshl_add_u64 v[216:217], s[16:17], 0, v[152:153]
	s_add_i32 m0, s18, 0x2000
	s_nop 0
	global_load_lds_dwordx4 v[216:217], off
	v_lshl_add_u64 v[216:217], v[220:221], 0, s[44:45]
	s_mov_b32 m0, s61
	s_nop 0
	global_load_lds_dwordx4 v[216:217], off
	v_lshl_add_u64 v[216:217], v[222:223], 0, s[44:45]
	s_mov_b32 m0, s66
	s_nop 0
	global_load_lds_dwordx4 v[216:217], off
	s_waitcnt vmcnt(8)
	s_waitcnt lgkmcnt(0)
	s_barrier
	s_waitcnt lgkmcnt(0)
	v_mfma_i32_16x16x64_i8 v[62:65], v[106:109], v[184:187], v[62:65]
	v_mfma_i32_16x16x64_i8 v[58:61], v[114:117], v[184:187], v[58:61]
	v_mfma_i32_16x16x64_i8 v[46:49], v[106:109], v[192:195], v[46:49]
	v_mfma_i32_16x16x64_i8 v[42:45], v[114:117], v[192:195], v[42:45]
	v_mfma_i32_16x16x64_i8 v[30:33], v[106:109], v[200:203], v[30:33]
	v_mfma_i32_16x16x64_i8 v[26:29], v[114:117], v[200:203], v[26:29]
	v_mfma_i32_16x16x64_i8 v[14:17], v[106:109], v[208:211], v[14:17]
	v_mfma_i32_16x16x64_i8 v[10:13], v[114:117], v[208:211], v[10:13]
	v_mfma_i32_16x16x64_i8 v[62:65], v[110:113], v[188:191], v[62:65]
	v_mfma_i32_16x16x64_i8 v[58:61], v[122:125], v[188:191], v[58:61]
	v_mfma_i32_16x16x64_i8 v[46:49], v[110:113], v[196:199], v[46:49]
	v_mfma_i32_16x16x64_i8 v[42:45], v[122:125], v[196:199], v[42:45]
	v_mfma_i32_16x16x64_i8 v[30:33], v[110:113], v[204:207], v[30:33]
	v_mfma_i32_16x16x64_i8 v[26:29], v[122:125], v[204:207], v[26:29]
	v_mfma_i32_16x16x64_i8 v[14:17], v[110:113], v[212:215], v[14:17]
	v_mfma_i32_16x16x64_i8 v[10:13], v[122:125], v[212:215], v[10:13]
	v_mfma_i32_16x16x64_i8 v[54:57], v[160:163], v[184:187], v[54:57]
	v_mfma_i32_16x16x64_i8 v[50:53], v[176:179], v[184:187], v[50:53]
	v_mfma_i32_16x16x64_i8 v[38:41], v[160:163], v[192:195], v[38:41]
	v_mfma_i32_16x16x64_i8 v[34:37], v[176:179], v[192:195], v[34:37]
	v_mfma_i32_16x16x64_i8 v[22:25], v[160:163], v[200:203], v[22:25]
	v_mfma_i32_16x16x64_i8 v[18:21], v[176:179], v[200:203], v[18:21]
	v_mfma_i32_16x16x64_i8 v[6:9], v[160:163], v[208:211], v[6:9]
	v_mfma_i32_16x16x64_i8 v[2:5], v[176:179], v[208:211], v[2:5]
	v_mfma_i32_16x16x64_i8 v[54:57], v[172:175], v[188:191], v[54:57]
	v_mfma_i32_16x16x64_i8 v[50:53], v[180:183], v[188:191], v[50:53]
	v_mfma_i32_16x16x64_i8 v[38:41], v[172:175], v[196:199], v[38:41]
	v_mfma_i32_16x16x64_i8 v[34:37], v[180:183], v[196:199], v[34:37]
	v_mfma_i32_16x16x64_i8 v[22:25], v[172:175], v[204:207], v[22:25]
	v_mfma_i32_16x16x64_i8 v[18:21], v[180:183], v[204:207], v[18:21]
	v_mfma_i32_16x16x64_i8 v[6:9], v[172:175], v[212:215], v[6:9]
	v_mfma_i32_16x16x64_i8 v[2:5], v[180:183], v[212:215], v[2:5]
	s_barrier
	s_add_i32 s13, s13, 2
	s_add_u32 s6, s6, 0x100
	s_addc_u32 s7, s7, 0
	s_add_u32 s8, s8, 0x100
	s_addc_u32 s12, s12, 0
	s_cmpk_gt_u32 s13, 0x53
	s_cbranch_scc0 .LBB0_362
	s_setprio 0
	s_and_b64 vcc, exec, s[46:47]
	s_cbranch_vccz .LBB0_365

.Lsp_p5:
.LBB0_541:
	ds_read_b128 v[146:149], v154
	ds_read_b128 v[158:161], v154 offset:1024
	ds_read_b128 v[162:165], v154 offset:2048
	ds_read_b128 v[166:169], v154 offset:3072
	ds_read_b128 v[170:173], v155
	ds_read_b128 v[174:177], v155 offset:1024
	ds_read_b128 v[178:181], v155 offset:2048
	ds_read_b128 v[182:185], v155 offset:3072
	s_add_u32 s18, s84, 0xfff00080
	s_addc_u32 s19, s85, -1
	s_cmp_eq_u32 s17, 60
	s_cselect_b32 s89, s5, s19
	s_cselect_b32 s88, s8, s18
	s_cselect_b32 s87, s9, s16
	s_cselect_b32 s86, s12, s13
	v_lshl_add_u64 v[218:219], s[84:85], 0, v[138:139]
	s_add_i32 m0, s56, 0xc000
	ds_read_b128 v[186:189], v156
	ds_read_b128 v[190:193], v156 offset:1024
	ds_read_b128 v[194:197], v156 offset:2048
	ds_read_b128 v[198:201], v156 offset:3072
	ds_read_b128 v[202:205], v156 offset:4096
	ds_read_b128 v[206:209], v156 offset:5120
	ds_read_b128 v[210:213], v156 offset:6144
	ds_read_b128 v[214:217], v156 offset:7168
	global_load_lds_dwordx4 v[218:219], off
	v_lshl_add_u64 v[218:219], s[84:85], 0, v[140:141]
	s_add_i32 m0, s56, 0xe000
	s_nop 0
	global_load_lds_dwordx4 v[218:219], off
	s_waitcnt vmcnt(8)
	s_waitcnt lgkmcnt(0)
	s_barrier
	s_waitcnt lgkmcnt(0)
	v_mfma_f32_16x16x32_bf16 v[126:129], v[146:149], v[186:189], v[126:129]
	v_mfma_f32_16x16x32_bf16 v[122:125], v[162:165], v[186:189], v[122:125]
	v_mfma_f32_16x16x32_bf16 v[110:113], v[146:149], v[194:197], v[110:113]
	v_mfma_f32_16x16x32_bf16 v[106:109], v[162:165], v[194:197], v[106:109]
	v_mfma_f32_16x16x32_bf16 v[94:97], v[146:149], v[202:205], v[94:97]
	v_mfma_f32_16x16x32_bf16 v[90:93], v[162:165], v[202:205], v[90:93]
	v_mfma_f32_16x16x32_bf16 v[78:81], v[146:149], v[210:213], v[78:81]
	v_mfma_f32_16x16x32_bf16 v[74:77], v[162:165], v[210:213], v[74:77]
	v_mfma_f32_16x16x32_bf16 v[126:129], v[158:161], v[190:193], v[126:129]
	v_mfma_f32_16x16x32_bf16 v[122:125], v[166:169], v[190:193], v[122:125]
	v_mfma_f32_16x16x32_bf16 v[110:113], v[158:161], v[198:201], v[110:113]
	v_mfma_f32_16x16x32_bf16 v[106:109], v[166:169], v[198:201], v[106:109]
	v_mfma_f32_16x16x32_bf16 v[94:97], v[158:161], v[206:209], v[94:97]
	v_mfma_f32_16x16x32_bf16 v[90:93], v[166:169], v[206:209], v[90:93]
	v_mfma_f32_16x16x32_bf16 v[78:81], v[158:161], v[214:217], v[78:81]
	v_mfma_f32_16x16x32_bf16 v[74:77], v[166:169], v[214:217], v[74:77]
	v_mfma_f32_16x16x32_bf16 v[118:121], v[170:173], v[186:189], v[118:121]
	v_mfma_f32_16x16x32_bf16 v[114:117], v[178:181], v[186:189], v[114:117]
	v_mfma_f32_16x16x32_bf16 v[102:105], v[170:173], v[194:197], v[102:105]
	v_mfma_f32_16x16x32_bf16 v[98:101], v[178:181], v[194:197], v[98:101]
	v_mfma_f32_16x16x32_bf16 v[86:89], v[170:173], v[202:205], v[86:89]
	v_mfma_f32_16x16x32_bf16 v[82:85], v[178:181], v[202:205], v[82:85]
	v_mfma_f32_16x16x32_bf16 v[70:73], v[170:173], v[210:213], v[70:73]
	v_mfma_f32_16x16x32_bf16 v[66:69], v[178:181], v[210:213], v[66:69]
	v_mfma_f32_16x16x32_bf16 v[118:121], v[174:177], v[190:193], v[118:121]
	v_mfma_f32_16x16x32_bf16 v[114:117], v[182:185], v[190:193], v[114:117]
	v_mfma_f32_16x16x32_bf16 v[102:105], v[174:177], v[198:201], v[102:105]
	v_mfma_f32_16x16x32_bf16 v[98:101], v[182:185], v[198:201], v[98:101]
	v_mfma_f32_16x16x32_bf16 v[86:89], v[174:177], v[206:209], v[86:89]
	v_mfma_f32_16x16x32_bf16 v[82:85], v[182:185], v[206:209], v[82:85]
	v_mfma_f32_16x16x32_bf16 v[70:73], v[174:177], v[214:217], v[70:73]
	v_mfma_f32_16x16x32_bf16 v[66:69], v[182:185], v[214:217], v[66:69]
	s_barrier
	s_add_i32 s18, s83, s35
	v_lshl_add_u64 v[218:219], s[86:87], 0, v[132:133]
	s_mov_b32 m0, s18
	ds_read_b128 v[186:189], v156 offset:16384
	ds_read_b128 v[190:193], v156 offset:17408
	ds_read_b128 v[194:197], v156 offset:18432
	ds_read_b128 v[198:201], v156 offset:19456
	ds_read_b128 v[202:205], v156 offset:20480
	ds_read_b128 v[206:209], v156 offset:21504
	ds_read_b128 v[210:213], v156 offset:22528
	ds_read_b128 v[214:217], v156 offset:23552
	global_load_lds_dwordx4 v[218:219], off
	s_add_i32 m0, s18, 0x2000
	s_add_u32 s18, s86, 0x100000
	v_lshl_add_u64 v[220:221], s[86:87], 0, v[136:137]
	s_addc_u32 s19, s87, 0
	s_add_i32 s20, s90, s35
	global_load_lds_dwordx4 v[220:221], off
	v_lshl_add_u64 v[222:223], s[18:19], 0, v[132:133]
	s_mov_b32 m0, s20
	v_lshl_add_u64 v[224:225], s[88:89], 0, v[134:135]
	global_load_lds_dwordx4 v[222:223], off
	v_lshl_add_u64 v[222:223], s[18:19], 0, v[136:137]
	s_add_i32 m0, s20, 0x2000
	s_nop 0
	global_load_lds_dwordx4 v[222:223], off
	v_lshl_add_u64 v[222:223], s[88:89], 0, v[130:131]
	s_mov_b32 m0, s56
	s_nop 0
	global_load_lds_dwordx4 v[222:223], off
	s_mov_b32 m0, s57
	s_nop 0
	global_load_lds_dwordx4 v[224:225], off
	s_waitcnt vmcnt(8)
	s_waitcnt lgkmcnt(0)
	s_barrier
	s_waitcnt lgkmcnt(0)
	v_mfma_f32_16x16x32_bf16 v[62:65], v[146:149], v[186:189], v[62:65]
	v_mfma_f32_16x16x32_bf16 v[58:61], v[162:165], v[186:189], v[58:61]
	v_mfma_f32_16x16x32_bf16 v[46:49], v[146:149], v[194:197], v[46:49]
	v_mfma_f32_16x16x32_bf16 v[42:45], v[162:165], v[194:197], v[42:45]
	v_mfma_f32_16x16x32_bf16 v[30:33], v[146:149], v[202:205], v[30:33]
	v_mfma_f32_16x16x32_bf16 v[26:29], v[162:165], v[202:205], v[26:29]
	v_mfma_f32_16x16x32_bf16 v[14:17], v[146:149], v[210:213], v[14:17]
	v_mfma_f32_16x16x32_bf16 v[10:13], v[162:165], v[210:213], v[10:13]
	v_mfma_f32_16x16x32_bf16 v[62:65], v[158:161], v[190:193], v[62:65]
	v_mfma_f32_16x16x32_bf16 v[58:61], v[166:169], v[190:193], v[58:61]
	v_mfma_f32_16x16x32_bf16 v[46:49], v[158:161], v[198:201], v[46:49]
	v_mfma_f32_16x16x32_bf16 v[42:45], v[166:169], v[198:201], v[42:45]
	v_mfma_f32_16x16x32_bf16 v[30:33], v[158:161], v[206:209], v[30:33]
	v_mfma_f32_16x16x32_bf16 v[26:29], v[166:169], v[206:209], v[26:29]
	v_mfma_f32_16x16x32_bf16 v[14:17], v[158:161], v[214:217], v[14:17]
	v_mfma_f32_16x16x32_bf16 v[10:13], v[166:169], v[214:217], v[10:13]
	v_mfma_f32_16x16x32_bf16 v[54:57], v[170:173], v[186:189], v[54:57]
	v_mfma_f32_16x16x32_bf16 v[50:53], v[178:181], v[186:189], v[50:53]
	v_mfma_f32_16x16x32_bf16 v[38:41], v[170:173], v[194:197], v[38:41]
	v_mfma_f32_16x16x32_bf16 v[34:37], v[178:181], v[194:197], v[34:37]
	v_mfma_f32_16x16x32_bf16 v[22:25], v[170:173], v[202:205], v[22:25]
	v_mfma_f32_16x16x32_bf16 v[18:21], v[178:181], v[202:205], v[18:21]
	v_mfma_f32_16x16x32_bf16 v[6:9], v[170:173], v[210:213], v[6:9]
	v_mfma_f32_16x16x32_bf16 v[2:5], v[178:181], v[210:213], v[2:5]
	v_mfma_f32_16x16x32_bf16 v[54:57], v[174:177], v[190:193], v[54:57]
	v_mfma_f32_16x16x32_bf16 v[50:53], v[182:185], v[190:193], v[50:53]
	v_mfma_f32_16x16x32_bf16 v[38:41], v[174:177], v[198:201], v[38:41]
	v_mfma_f32_16x16x32_bf16 v[34:37], v[182:185], v[198:201], v[34:37]
	v_mfma_f32_16x16x32_bf16 v[22:25], v[174:177], v[206:209], v[22:25]
	v_mfma_f32_16x16x32_bf16 v[18:21], v[182:185], v[206:209], v[18:21]
	v_mfma_f32_16x16x32_bf16 v[6:9], v[174:177], v[214:217], v[6:9]
	v_mfma_f32_16x16x32_bf16 v[2:5], v[182:185], v[214:217], v[2:5]
	s_barrier
	s_add_i32 s20, 0, 0x18000
	v_add_u32_e32 v150, s20, v151
	s_add_i32 s21, 0, 0x1c000
	ds_read_b128 v[146:149], v150
	ds_read_b128 v[158:161], v150 offset:1024
	ds_read_b128 v[162:165], v150 offset:2048
	ds_read_b128 v[166:169], v150 offset:3072
	v_add_u32_e32 v150, s21, v151
	ds_read_b128 v[170:173], v150
	ds_read_b128 v[174:177], v150 offset:1024
	ds_read_b128 v[178:181], v150 offset:2048
	ds_read_b128 v[182:185], v150 offset:3072
	s_add_u32 s18, s88, 0x100000
	s_addc_u32 s19, s89, 0
	s_mov_b32 m0, s58
	v_lshl_add_u64 v[228:229], s[18:19], 0, v[130:131]
	ds_read_b128 v[186:189], v156 offset:32768
	ds_read_b128 v[190:193], v156 offset:33792
	ds_read_b128 v[194:197], v156 offset:34816
	ds_read_b128 v[198:201], v156 offset:35840
	ds_read_b128 v[202:205], v156 offset:36864
	ds_read_b128 v[206:209], v156 offset:37888
	ds_read_b128 v[210:213], v156 offset:38912
	ds_read_b128 v[214:217], v156 offset:39936
	global_load_lds_dwordx4 v[228:229], off
	v_lshl_add_u64 v[228:229], s[18:19], 0, v[134:135]
	s_mov_b32 m0, s59
	s_nop 0
	global_load_lds_dwordx4 v[228:229], off
	s_waitcnt vmcnt(8)
	s_waitcnt lgkmcnt(0)
	s_barrier
	s_waitcnt lgkmcnt(0)
	v_mfma_f32_16x16x32_bf16 v[126:129], v[146:149], v[186:189], v[126:129]
	v_mfma_f32_16x16x32_bf16 v[122:125], v[162:165], v[186:189], v[122:125]
	v_mfma_f32_16x16x32_bf16 v[110:113], v[146:149], v[194:197], v[110:113]
	v_mfma_f32_16x16x32_bf16 v[106:109], v[162:165], v[194:197], v[106:109]
	v_mfma_f32_16x16x32_bf16 v[94:97], v[146:149], v[202:205], v[94:97]
	v_mfma_f32_16x16x32_bf16 v[90:93], v[162:165], v[202:205], v[90:93]
	v_mfma_f32_16x16x32_bf16 v[78:81], v[146:149], v[210:213], v[78:81]
	v_mfma_f32_16x16x32_bf16 v[74:77], v[162:165], v[210:213], v[74:77]
	v_mfma_f32_16x16x32_bf16 v[126:129], v[158:161], v[190:193], v[126:129]
	v_mfma_f32_16x16x32_bf16 v[122:125], v[166:169], v[190:193], v[122:125]
	v_mfma_f32_16x16x32_bf16 v[110:113], v[158:161], v[198:201], v[110:113]
	v_mfma_f32_16x16x32_bf16 v[106:109], v[166:169], v[198:201], v[106:109]
	v_mfma_f32_16x16x32_bf16 v[94:97], v[158:161], v[206:209], v[94:97]
	v_mfma_f32_16x16x32_bf16 v[90:93], v[166:169], v[206:209], v[90:93]
	v_mfma_f32_16x16x32_bf16 v[78:81], v[158:161], v[214:217], v[78:81]
	v_mfma_f32_16x16x32_bf16 v[74:77], v[166:169], v[214:217], v[74:77]
	v_mfma_f32_16x16x32_bf16 v[118:121], v[170:173], v[186:189], v[118:121]
	v_mfma_f32_16x16x32_bf16 v[114:117], v[178:181], v[186:189], v[114:117]
	v_mfma_f32_16x16x32_bf16 v[102:105], v[170:173], v[194:197], v[102:105]
	v_mfma_f32_16x16x32_bf16 v[98:101], v[178:181], v[194:197], v[98:101]
	v_mfma_f32_16x16x32_bf16 v[86:89], v[170:173], v[202:205], v[86:89]
	v_mfma_f32_16x16x32_bf16 v[82:85], v[178:181], v[202:205], v[82:85]
	v_mfma_f32_16x16x32_bf16 v[70:73], v[170:173], v[210:213], v[70:73]
	v_mfma_f32_16x16x32_bf16 v[66:69], v[178:181], v[210:213], v[66:69]
	v_mfma_f32_16x16x32_bf16 v[118:121], v[174:177], v[190:193], v[118:121]
	v_mfma_f32_16x16x32_bf16 v[114:117], v[182:185], v[190:193], v[114:117]
	v_mfma_f32_16x16x32_bf16 v[102:105], v[174:177], v[198:201], v[102:105]
	v_mfma_f32_16x16x32_bf16 v[98:101], v[182:185], v[198:201], v[98:101]
	v_mfma_f32_16x16x32_bf16 v[86:89], v[174:177], v[206:209], v[86:89]
	v_mfma_f32_16x16x32_bf16 v[82:85], v[182:185], v[206:209], v[82:85]
	v_mfma_f32_16x16x32_bf16 v[70:73], v[174:177], v[214:217], v[70:73]
	v_mfma_f32_16x16x32_bf16 v[66:69], v[182:185], v[214:217], v[66:69]
	s_barrier
	s_add_i32 s18, s20, s35
	v_lshl_add_u64 v[218:219], v[218:219], 0, s[40:41]
	s_mov_b32 m0, s18
	ds_read_b128 v[186:189], v156 offset:49152
	ds_read_b128 v[190:193], v156 offset:50176
	ds_read_b128 v[194:197], v156 offset:51200
	ds_read_b128 v[198:201], v156 offset:52224
	ds_read_b128 v[202:205], v156 offset:53248
	ds_read_b128 v[206:209], v156 offset:54272
	ds_read_b128 v[210:213], v156 offset:55296
	ds_read_b128 v[214:217], v156 offset:56320
	global_load_lds_dwordx4 v[218:219], off
	s_add_i32 m0, s18, 0x2000
	s_add_u32 s18, s86, 0x100080
	v_lshl_add_u64 v[218:219], v[220:221], 0, s[40:41]
	s_addc_u32 s19, s87, 0
	s_add_i32 s20, s21, s35
	global_load_lds_dwordx4 v[218:219], off
	v_lshl_add_u64 v[218:219], s[18:19], 0, v[132:133]
	s_mov_b32 m0, s20
	s_nop 0
	global_load_lds_dwordx4 v[218:219], off
	v_lshl_add_u64 v[218:219], s[18:19], 0, v[136:137]
	s_add_i32 m0, s20, 0x2000
	s_nop 0
	global_load_lds_dwordx4 v[218:219], off
	v_lshl_add_u64 v[218:219], v[222:223], 0, s[40:41]
	s_mov_b32 m0, s66
	s_nop 0
	global_load_lds_dwordx4 v[218:219], off
	v_lshl_add_u64 v[218:219], v[224:225], 0, s[40:41]
	s_mov_b32 m0, s67
	s_nop 0
	global_load_lds_dwordx4 v[218:219], off
	s_waitcnt vmcnt(8)
	s_waitcnt lgkmcnt(0)
	s_barrier
	s_waitcnt lgkmcnt(0)
	v_mfma_f32_16x16x32_bf16 v[62:65], v[146:149], v[186:189], v[62:65]
	v_mfma_f32_16x16x32_bf16 v[58:61], v[162:165], v[186:189], v[58:61]
	v_mfma_f32_16x16x32_bf16 v[46:49], v[146:149], v[194:197], v[46:49]
	v_mfma_f32_16x16x32_bf16 v[42:45], v[162:165], v[194:197], v[42:45]
	v_mfma_f32_16x16x32_bf16 v[30:33], v[146:149], v[202:205], v[30:33]
	v_mfma_f32_16x16x32_bf16 v[26:29], v[162:165], v[202:205], v[26:29]
	v_mfma_f32_16x16x32_bf16 v[14:17], v[146:149], v[210:213], v[14:17]
	v_mfma_f32_16x16x32_bf16 v[10:13], v[162:165], v[210:213], v[10:13]
	v_mfma_f32_16x16x32_bf16 v[62:65], v[158:161], v[190:193], v[62:65]
	v_mfma_f32_16x16x32_bf16 v[58:61], v[166:169], v[190:193], v[58:61]
	v_mfma_f32_16x16x32_bf16 v[46:49], v[158:161], v[198:201], v[46:49]
	v_mfma_f32_16x16x32_bf16 v[42:45], v[166:169], v[198:201], v[42:45]
	v_mfma_f32_16x16x32_bf16 v[30:33], v[158:161], v[206:209], v[30:33]
	v_mfma_f32_16x16x32_bf16 v[26:29], v[166:169], v[206:209], v[26:29]
	v_mfma_f32_16x16x32_bf16 v[14:17], v[158:161], v[214:217], v[14:17]
	v_mfma_f32_16x16x32_bf16 v[10:13], v[166:169], v[214:217], v[10:13]
	v_mfma_f32_16x16x32_bf16 v[54:57], v[170:173], v[186:189], v[54:57]
	v_mfma_f32_16x16x32_bf16 v[50:53], v[178:181], v[186:189], v[50:53]
	v_mfma_f32_16x16x32_bf16 v[38:41], v[170:173], v[194:197], v[38:41]
	v_mfma_f32_16x16x32_bf16 v[34:37], v[178:181], v[194:197], v[34:37]
	v_mfma_f32_16x16x32_bf16 v[22:25], v[170:173], v[202:205], v[22:25]
	v_mfma_f32_16x16x32_bf16 v[18:21], v[178:181], v[202:205], v[18:21]
	v_mfma_f32_16x16x32_bf16 v[6:9], v[170:173], v[210:213], v[6:9]
	v_mfma_f32_16x16x32_bf16 v[2:5], v[178:181], v[210:213], v[2:5]
	v_mfma_f32_16x16x32_bf16 v[54:57], v[174:177], v[190:193], v[54:57]
	v_mfma_f32_16x16x32_bf16 v[50:53], v[182:185], v[190:193], v[50:53]
	v_mfma_f32_16x16x32_bf16 v[38:41], v[174:177], v[198:201], v[38:41]
	v_mfma_f32_16x16x32_bf16 v[34:37], v[182:185], v[198:201], v[34:37]
	v_mfma_f32_16x16x32_bf16 v[22:25], v[174:177], v[206:209], v[22:25]
	v_mfma_f32_16x16x32_bf16 v[18:21], v[182:185], v[206:209], v[18:21]
	v_mfma_f32_16x16x32_bf16 v[6:9], v[174:177], v[214:217], v[6:9]
	v_mfma_f32_16x16x32_bf16 v[2:5], v[182:185], v[214:217], v[2:5]
	s_barrier
	s_add_i32 s17, s17, 2
	s_add_u32 s84, s84, 0x100
	s_addc_u32 s85, s85, 0
	s_add_u32 s13, s13, 0x100
	s_addc_u32 s16, s16, 0
	s_cmp_gt_u32 s17, 61
	s_cbranch_scc0 .LBB0_541
	s_setprio 0
	s_and_b64 vcc, exec, s[42:43]
	s_cbranch_vccz .LBB0_544

.Lsp_p11:
.LBB0_1015:
	ds_read_b128 v[146:149], v156
	ds_read_b128 v[150:153], v156 offset:1024
	ds_read_b128 v[160:163], v156 offset:2048
	ds_read_b128 v[164:167], v156 offset:3072
	ds_read_b128 v[168:171], v157
	ds_read_b128 v[172:175], v157 offset:1024
	ds_read_b128 v[176:179], v157 offset:2048
	ds_read_b128 v[180:183], v157 offset:3072
	s_add_u32 s44, s42, 0xfff80080
	s_addc_u32 s45, s43, -1
	s_cmp_eq_u32 s67, 28
	s_cselect_b32 s47, s8, s45
	s_cselect_b32 s46, s9, s44
	s_cselect_b32 s45, s21, s66
	s_cselect_b32 s44, s23, s61
	v_lshl_add_u64 v[216:217], s[42:43], 0, v[138:139]
	s_add_i32 m0, s41, 0xc000
	ds_read_b128 v[184:187], v158
	ds_read_b128 v[188:191], v158 offset:1024
	ds_read_b128 v[192:195], v158 offset:2048
	ds_read_b128 v[196:199], v158 offset:3072
	ds_read_b128 v[200:203], v158 offset:4096
	ds_read_b128 v[204:207], v158 offset:5120
	ds_read_b128 v[208:211], v158 offset:6144
	ds_read_b128 v[212:215], v158 offset:7168
	global_load_lds_dwordx4 v[216:217], off
	v_lshl_add_u64 v[216:217], s[42:43], 0, v[140:141]
	s_add_i32 m0, s41, 0xe000
	s_nop 0
	global_load_lds_dwordx4 v[216:217], off
	s_waitcnt vmcnt(8)
	s_waitcnt lgkmcnt(0)
	s_barrier
	s_waitcnt lgkmcnt(0)
	v_mfma_i32_16x16x64_i8 v[126:129], v[146:149], v[184:187], v[126:129]
	v_mfma_i32_16x16x64_i8 v[122:125], v[160:163], v[184:187], v[122:125]
	v_mfma_i32_16x16x64_i8 v[110:113], v[146:149], v[192:195], v[110:113]
	v_mfma_i32_16x16x64_i8 v[106:109], v[160:163], v[192:195], v[106:109]
	v_mfma_i32_16x16x64_i8 v[94:97], v[146:149], v[200:203], v[94:97]
	v_mfma_i32_16x16x64_i8 v[90:93], v[160:163], v[200:203], v[90:93]
	v_mfma_i32_16x16x64_i8 v[78:81], v[146:149], v[208:211], v[78:81]
	v_mfma_i32_16x16x64_i8 v[74:77], v[160:163], v[208:211], v[74:77]
	v_mfma_i32_16x16x64_i8 v[126:129], v[150:153], v[188:191], v[126:129]
	v_mfma_i32_16x16x64_i8 v[122:125], v[164:167], v[188:191], v[122:125]
	v_mfma_i32_16x16x64_i8 v[110:113], v[150:153], v[196:199], v[110:113]
	v_mfma_i32_16x16x64_i8 v[106:109], v[164:167], v[196:199], v[106:109]
	v_mfma_i32_16x16x64_i8 v[94:97], v[150:153], v[204:207], v[94:97]
	v_mfma_i32_16x16x64_i8 v[90:93], v[164:167], v[204:207], v[90:93]
	v_mfma_i32_16x16x64_i8 v[78:81], v[150:153], v[212:215], v[78:81]
	v_mfma_i32_16x16x64_i8 v[74:77], v[164:167], v[212:215], v[74:77]
	v_mfma_i32_16x16x64_i8 v[118:121], v[168:171], v[184:187], v[118:121]
	v_mfma_i32_16x16x64_i8 v[114:117], v[176:179], v[184:187], v[114:117]
	v_mfma_i32_16x16x64_i8 v[102:105], v[168:171], v[192:195], v[102:105]
	v_mfma_i32_16x16x64_i8 v[98:101], v[176:179], v[192:195], v[98:101]
	v_mfma_i32_16x16x64_i8 v[86:89], v[168:171], v[200:203], v[86:89]
	v_mfma_i32_16x16x64_i8 v[82:85], v[176:179], v[200:203], v[82:85]
	v_mfma_i32_16x16x64_i8 v[70:73], v[168:171], v[208:211], v[70:73]
	v_mfma_i32_16x16x64_i8 v[66:69], v[176:179], v[208:211], v[66:69]
	v_mfma_i32_16x16x64_i8 v[118:121], v[172:175], v[188:191], v[118:121]
	v_mfma_i32_16x16x64_i8 v[114:117], v[180:183], v[188:191], v[114:117]
	v_mfma_i32_16x16x64_i8 v[102:105], v[172:175], v[196:199], v[102:105]
	v_mfma_i32_16x16x64_i8 v[98:101], v[180:183], v[196:199], v[98:101]
	v_mfma_i32_16x16x64_i8 v[86:89], v[172:175], v[204:207], v[86:89]
	v_mfma_i32_16x16x64_i8 v[82:85], v[180:183], v[204:207], v[82:85]
	v_mfma_i32_16x16x64_i8 v[70:73], v[172:175], v[212:215], v[70:73]
	v_mfma_i32_16x16x64_i8 v[66:69], v[180:183], v[212:215], v[66:69]
	s_barrier
	s_add_i32 s68, s56, s19
	v_lshl_add_u64 v[216:217], s[44:45], 0, v[134:135]
	s_mov_b32 m0, s68
	ds_read_b128 v[184:187], v158 offset:16384
	ds_read_b128 v[188:191], v158 offset:17408
	ds_read_b128 v[192:195], v158 offset:18432
	ds_read_b128 v[196:199], v158 offset:19456
	ds_read_b128 v[200:203], v158 offset:20480
	ds_read_b128 v[204:207], v158 offset:21504
	ds_read_b128 v[208:211], v158 offset:22528
	ds_read_b128 v[212:215], v158 offset:23552
	global_load_lds_dwordx4 v[216:217], off
	s_add_i32 m0, s68, 0x2000
	s_add_u32 s68, s44, 0x80000
	v_lshl_add_u64 v[218:219], s[44:45], 0, v[130:131]
	s_addc_u32 s69, s45, 0
	s_add_i32 s72, s57, s19
	global_load_lds_dwordx4 v[218:219], off
	v_lshl_add_u64 v[220:221], s[68:69], 0, v[134:135]
	s_mov_b32 m0, s72
	v_lshl_add_u64 v[222:223], s[46:47], 0, v[132:133]
	global_load_lds_dwordx4 v[220:221], off
	v_lshl_add_u64 v[220:221], s[68:69], 0, v[130:131]
	s_add_i32 m0, s72, 0x2000
	s_nop 0
	global_load_lds_dwordx4 v[220:221], off
	v_lshl_add_u64 v[220:221], s[46:47], 0, v[136:137]
	s_mov_b32 m0, s41
	s_nop 0
	global_load_lds_dwordx4 v[220:221], off
	s_mov_b32 m0, s49
	s_nop 0
	global_load_lds_dwordx4 v[222:223], off
	s_waitcnt vmcnt(8)
	s_waitcnt lgkmcnt(0)
	s_barrier
	s_waitcnt lgkmcnt(0)
	v_mfma_i32_16x16x64_i8 v[62:65], v[146:149], v[184:187], v[62:65]
	v_mfma_i32_16x16x64_i8 v[58:61], v[160:163], v[184:187], v[58:61]
	v_mfma_i32_16x16x64_i8 v[46:49], v[146:149], v[192:195], v[46:49]
	v_mfma_i32_16x16x64_i8 v[42:45], v[160:163], v[192:195], v[42:45]
	v_mfma_i32_16x16x64_i8 v[30:33], v[146:149], v[200:203], v[30:33]
	v_mfma_i32_16x16x64_i8 v[26:29], v[160:163], v[200:203], v[26:29]
	v_mfma_i32_16x16x64_i8 v[14:17], v[146:149], v[208:211], v[14:17]
	v_mfma_i32_16x16x64_i8 v[10:13], v[160:163], v[208:211], v[10:13]
	v_mfma_i32_16x16x64_i8 v[62:65], v[150:153], v[188:191], v[62:65]
	v_mfma_i32_16x16x64_i8 v[58:61], v[164:167], v[188:191], v[58:61]
	v_mfma_i32_16x16x64_i8 v[46:49], v[150:153], v[196:199], v[46:49]
	v_mfma_i32_16x16x64_i8 v[42:45], v[164:167], v[196:199], v[42:45]
	v_mfma_i32_16x16x64_i8 v[30:33], v[150:153], v[204:207], v[30:33]
	v_mfma_i32_16x16x64_i8 v[26:29], v[164:167], v[204:207], v[26:29]
	v_mfma_i32_16x16x64_i8 v[14:17], v[150:153], v[212:215], v[14:17]
	v_mfma_i32_16x16x64_i8 v[10:13], v[164:167], v[212:215], v[10:13]
	v_mfma_i32_16x16x64_i8 v[54:57], v[168:171], v[184:187], v[54:57]
	v_mfma_i32_16x16x64_i8 v[50:53], v[176:179], v[184:187], v[50:53]
	v_mfma_i32_16x16x64_i8 v[38:41], v[168:171], v[192:195], v[38:41]
	v_mfma_i32_16x16x64_i8 v[34:37], v[176:179], v[192:195], v[34:37]
	v_mfma_i32_16x16x64_i8 v[22:25], v[168:171], v[200:203], v[22:25]
	v_mfma_i32_16x16x64_i8 v[18:21], v[176:179], v[200:203], v[18:21]
	v_mfma_i32_16x16x64_i8 v[6:9], v[168:171], v[208:211], v[6:9]
	v_mfma_i32_16x16x64_i8 v[2:5], v[176:179], v[208:211], v[2:5]
	v_mfma_i32_16x16x64_i8 v[54:57], v[172:175], v[188:191], v[54:57]
	v_mfma_i32_16x16x64_i8 v[50:53], v[180:183], v[188:191], v[50:53]
	v_mfma_i32_16x16x64_i8 v[38:41], v[172:175], v[196:199], v[38:41]
	v_mfma_i32_16x16x64_i8 v[34:37], v[180:183], v[196:199], v[34:37]
	v_mfma_i32_16x16x64_i8 v[22:25], v[172:175], v[204:207], v[22:25]
	v_mfma_i32_16x16x64_i8 v[18:21], v[180:183], v[204:207], v[18:21]
	v_mfma_i32_16x16x64_i8 v[6:9], v[172:175], v[212:215], v[6:9]
	v_mfma_i32_16x16x64_i8 v[2:5], v[180:183], v[212:215], v[2:5]
	s_barrier
	s_add_i32 s68, 0, 0x18000
	v_add_u32_e32 v159, s68, v154
	s_add_i32 s69, 0, 0x1c000
	ds_read_b128 v[146:149], v159
	ds_read_b128 v[150:153], v159 offset:1024
	ds_read_b128 v[160:163], v159 offset:2048
	ds_read_b128 v[164:167], v159 offset:3072
	v_add_u32_e32 v159, s69, v154
	ds_read_b128 v[168:171], v159
	ds_read_b128 v[172:175], v159 offset:1024
	ds_read_b128 v[176:179], v159 offset:2048
	ds_read_b128 v[180:183], v159 offset:3072
	s_add_u32 s46, s46, 0x80000
	s_addc_u32 s47, s47, 0
	s_mov_b32 m0, s50
	v_lshl_add_u64 v[224:225], s[46:47], 0, v[136:137]
	ds_read_b128 v[184:187], v158 offset:32768
	ds_read_b128 v[188:191], v158 offset:33792
	ds_read_b128 v[192:195], v158 offset:34816
	ds_read_b128 v[196:199], v158 offset:35840
	ds_read_b128 v[200:203], v158 offset:36864
	ds_read_b128 v[204:207], v158 offset:37888
	ds_read_b128 v[208:211], v158 offset:38912
	ds_read_b128 v[212:215], v158 offset:39936
	global_load_lds_dwordx4 v[224:225], off
	v_lshl_add_u64 v[224:225], s[46:47], 0, v[132:133]
	s_mov_b32 m0, s51
	s_nop 0
	global_load_lds_dwordx4 v[224:225], off
	s_waitcnt vmcnt(8)
	s_waitcnt lgkmcnt(0)
	s_barrier
	s_waitcnt lgkmcnt(0)
	v_mfma_i32_16x16x64_i8 v[126:129], v[146:149], v[184:187], v[126:129]
	v_mfma_i32_16x16x64_i8 v[122:125], v[160:163], v[184:187], v[122:125]
	v_mfma_i32_16x16x64_i8 v[110:113], v[146:149], v[192:195], v[110:113]
	v_mfma_i32_16x16x64_i8 v[106:109], v[160:163], v[192:195], v[106:109]
	v_mfma_i32_16x16x64_i8 v[94:97], v[146:149], v[200:203], v[94:97]
	v_mfma_i32_16x16x64_i8 v[90:93], v[160:163], v[200:203], v[90:93]
	v_mfma_i32_16x16x64_i8 v[78:81], v[146:149], v[208:211], v[78:81]
	v_mfma_i32_16x16x64_i8 v[74:77], v[160:163], v[208:211], v[74:77]
	v_mfma_i32_16x16x64_i8 v[126:129], v[150:153], v[188:191], v[126:129]
	v_mfma_i32_16x16x64_i8 v[122:125], v[164:167], v[188:191], v[122:125]
	v_mfma_i32_16x16x64_i8 v[110:113], v[150:153], v[196:199], v[110:113]
	v_mfma_i32_16x16x64_i8 v[106:109], v[164:167], v[196:199], v[106:109]
	v_mfma_i32_16x16x64_i8 v[94:97], v[150:153], v[204:207], v[94:97]
	v_mfma_i32_16x16x64_i8 v[90:93], v[164:167], v[204:207], v[90:93]
	v_mfma_i32_16x16x64_i8 v[78:81], v[150:153], v[212:215], v[78:81]
	v_mfma_i32_16x16x64_i8 v[74:77], v[164:167], v[212:215], v[74:77]
	v_mfma_i32_16x16x64_i8 v[118:121], v[168:171], v[184:187], v[118:121]
	v_mfma_i32_16x16x64_i8 v[114:117], v[176:179], v[184:187], v[114:117]
	v_mfma_i32_16x16x64_i8 v[102:105], v[168:171], v[192:195], v[102:105]
	v_mfma_i32_16x16x64_i8 v[98:101], v[176:179], v[192:195], v[98:101]
	v_mfma_i32_16x16x64_i8 v[86:89], v[168:171], v[200:203], v[86:89]
	v_mfma_i32_16x16x64_i8 v[82:85], v[176:179], v[200:203], v[82:85]
	v_mfma_i32_16x16x64_i8 v[70:73], v[168:171], v[208:211], v[70:73]
	v_mfma_i32_16x16x64_i8 v[66:69], v[176:179], v[208:211], v[66:69]
	v_mfma_i32_16x16x64_i8 v[118:121], v[172:175], v[188:191], v[118:121]
	v_mfma_i32_16x16x64_i8 v[114:117], v[180:183], v[188:191], v[114:117]
	v_mfma_i32_16x16x64_i8 v[102:105], v[172:175], v[196:199], v[102:105]
	v_mfma_i32_16x16x64_i8 v[98:101], v[180:183], v[196:199], v[98:101]
	v_mfma_i32_16x16x64_i8 v[86:89], v[172:175], v[204:207], v[86:89]
	v_mfma_i32_16x16x64_i8 v[82:85], v[180:183], v[204:207], v[82:85]
	v_mfma_i32_16x16x64_i8 v[70:73], v[172:175], v[212:215], v[70:73]
	v_mfma_i32_16x16x64_i8 v[66:69], v[180:183], v[212:215], v[66:69]
	s_barrier
	s_add_i32 s46, s68, s19
	v_lshl_add_u64 v[216:217], v[216:217], 0, s[4:5]
	s_mov_b32 m0, s46
	ds_read_b128 v[184:187], v158 offset:49152
	ds_read_b128 v[188:191], v158 offset:50176
	ds_read_b128 v[192:195], v158 offset:51200
	ds_read_b128 v[196:199], v158 offset:52224
	ds_read_b128 v[200:203], v158 offset:53248
	ds_read_b128 v[204:207], v158 offset:54272
	ds_read_b128 v[208:211], v158 offset:55296
	ds_read_b128 v[212:215], v158 offset:56320
	global_load_lds_dwordx4 v[216:217], off
	s_add_i32 m0, s46, 0x2000
	s_add_u32 s44, s44, 0x80080
	v_lshl_add_u64 v[216:217], v[218:219], 0, s[4:5]
	s_addc_u32 s45, s45, 0
	s_add_i32 s46, s69, s19
	global_load_lds_dwordx4 v[216:217], off
	v_lshl_add_u64 v[216:217], s[44:45], 0, v[134:135]
	s_mov_b32 m0, s46
	s_nop 0
	global_load_lds_dwordx4 v[216:217], off
	v_lshl_add_u64 v[216:217], s[44:45], 0, v[130:131]
	s_add_i32 m0, s46, 0x2000
	s_nop 0
	global_load_lds_dwordx4 v[216:217], off
	v_lshl_add_u64 v[216:217], v[220:221], 0, s[4:5]
	s_mov_b32 m0, s53
	s_nop 0
	global_load_lds_dwordx4 v[216:217], off
	v_lshl_add_u64 v[216:217], v[222:223], 0, s[4:5]
	s_mov_b32 m0, s54
	s_nop 0
	global_load_lds_dwordx4 v[216:217], off
	s_waitcnt vmcnt(8)
	s_waitcnt lgkmcnt(0)
	s_barrier
	s_waitcnt lgkmcnt(0)
	v_mfma_i32_16x16x64_i8 v[62:65], v[146:149], v[184:187], v[62:65]
	v_mfma_i32_16x16x64_i8 v[58:61], v[160:163], v[184:187], v[58:61]
	v_mfma_i32_16x16x64_i8 v[46:49], v[146:149], v[192:195], v[46:49]
	v_mfma_i32_16x16x64_i8 v[42:45], v[160:163], v[192:195], v[42:45]
	v_mfma_i32_16x16x64_i8 v[30:33], v[146:149], v[200:203], v[30:33]
	v_mfma_i32_16x16x64_i8 v[26:29], v[160:163], v[200:203], v[26:29]
	v_mfma_i32_16x16x64_i8 v[14:17], v[146:149], v[208:211], v[14:17]
	v_mfma_i32_16x16x64_i8 v[10:13], v[160:163], v[208:211], v[10:13]
	v_mfma_i32_16x16x64_i8 v[62:65], v[150:153], v[188:191], v[62:65]
	v_mfma_i32_16x16x64_i8 v[58:61], v[164:167], v[188:191], v[58:61]
	v_mfma_i32_16x16x64_i8 v[46:49], v[150:153], v[196:199], v[46:49]
	v_mfma_i32_16x16x64_i8 v[42:45], v[164:167], v[196:199], v[42:45]
	v_mfma_i32_16x16x64_i8 v[30:33], v[150:153], v[204:207], v[30:33]
	v_mfma_i32_16x16x64_i8 v[26:29], v[164:167], v[204:207], v[26:29]
	v_mfma_i32_16x16x64_i8 v[14:17], v[150:153], v[212:215], v[14:17]
	v_mfma_i32_16x16x64_i8 v[10:13], v[164:167], v[212:215], v[10:13]
	v_mfma_i32_16x16x64_i8 v[54:57], v[168:171], v[184:187], v[54:57]
	v_mfma_i32_16x16x64_i8 v[50:53], v[176:179], v[184:187], v[50:53]
	v_mfma_i32_16x16x64_i8 v[38:41], v[168:171], v[192:195], v[38:41]
	v_mfma_i32_16x16x64_i8 v[34:37], v[176:179], v[192:195], v[34:37]
	v_mfma_i32_16x16x64_i8 v[22:25], v[168:171], v[200:203], v[22:25]
	v_mfma_i32_16x16x64_i8 v[18:21], v[176:179], v[200:203], v[18:21]
	v_mfma_i32_16x16x64_i8 v[6:9], v[168:171], v[208:211], v[6:9]
	v_mfma_i32_16x16x64_i8 v[2:5], v[176:179], v[208:211], v[2:5]
	v_mfma_i32_16x16x64_i8 v[54:57], v[172:175], v[188:191], v[54:57]
	v_mfma_i32_16x16x64_i8 v[50:53], v[180:183], v[188:191], v[50:53]
	v_mfma_i32_16x16x64_i8 v[38:41], v[172:175], v[196:199], v[38:41]
	v_mfma_i32_16x16x64_i8 v[34:37], v[180:183], v[196:199], v[34:37]
	v_mfma_i32_16x16x64_i8 v[22:25], v[172:175], v[204:207], v[22:25]
	v_mfma_i32_16x16x64_i8 v[18:21], v[180:183], v[204:207], v[18:21]
	v_mfma_i32_16x16x64_i8 v[6:9], v[172:175], v[212:215], v[6:9]
	v_mfma_i32_16x16x64_i8 v[2:5], v[180:183], v[212:215], v[2:5]
	s_barrier
	s_add_i32 s67, s67, 2
	s_add_u32 s42, s42, 0x100
	s_addc_u32 s43, s43, 0
	s_add_u32 s61, s61, 0x100
	s_addc_u32 s66, s66, 0
	s_cmp_gt_u32 s67, 29
	s_cbranch_scc0 .LBB0_1015
	s_setprio 0
	s_and_b64 vcc, exec, s[12:13]
	s_cbranch_vccz .LBB0_1018

.Lsp_p13:
.LBB0_1166:
	ds_read_b128 v[104:107], v167
	ds_read_b128 v[108:111], v167 offset:1024
	ds_read_b128 v[112:115], v167 offset:2048
	ds_read_b128 v[120:123], v167 offset:3072
	ds_read_b128 v[158:161], v168
	ds_read_b128 v[170:173], v168 offset:1024
	ds_read_b128 v[174:177], v168 offset:2048
	ds_read_b128 v[178:181], v168 offset:3072
	s_add_u32 s26, s6, 0xffea8080
	s_addc_u32 s27, s7, -1
	s_cmpk_eq_i32 s55, 0x52
	s_cselect_b32 s29, s23, s27
	s_cselect_b32 s28, s22, s26
	s_cselect_b32 s27, s25, s9
	s_cselect_b32 s26, s24, s8
	v_lshl_add_u64 v[214:215], s[6:7], 0, v[152:153]
	s_add_i32 m0, s38, 0xc000
	ds_read_b128 v[182:185], v169
	ds_read_b128 v[186:189], v169 offset:1024
	ds_read_b128 v[190:193], v169 offset:2048
	ds_read_b128 v[194:197], v169 offset:3072
	ds_read_b128 v[198:201], v169 offset:4096
	ds_read_b128 v[202:205], v169 offset:5120
	ds_read_b128 v[206:209], v169 offset:6144
	ds_read_b128 v[210:213], v169 offset:7168
	global_load_lds_dwordx4 v[214:215], off
	v_lshl_add_u64 v[214:215], s[6:7], 0, v[154:155]
	s_add_i32 m0, s38, 0xe000
	s_nop 0
	global_load_lds_dwordx4 v[214:215], off
	s_waitcnt vmcnt(8)
	s_waitcnt lgkmcnt(0)
	s_barrier
	s_waitcnt lgkmcnt(0)
	v_mfma_i32_16x16x64_i8 v[140:143], v[104:107], v[182:185], v[140:143]
	v_mfma_i32_16x16x64_i8 v[136:139], v[112:115], v[182:185], v[136:139]
	v_mfma_i32_16x16x64_i8 v[124:127], v[104:107], v[190:193], v[124:127]
	v_mfma_i32_16x16x64_i8 v[116:119], v[112:115], v[190:193], v[116:119]
	v_mfma_i32_16x16x64_i8 v[92:95], v[104:107], v[198:201], v[92:95]
	v_mfma_i32_16x16x64_i8 v[88:91], v[112:115], v[198:201], v[88:91]
	v_mfma_i32_16x16x64_i8 v[76:79], v[104:107], v[206:209], v[76:79]
	v_mfma_i32_16x16x64_i8 v[72:75], v[112:115], v[206:209], v[72:75]
	v_mfma_i32_16x16x64_i8 v[140:143], v[108:111], v[186:189], v[140:143]
	v_mfma_i32_16x16x64_i8 v[136:139], v[120:123], v[186:189], v[136:139]
	v_mfma_i32_16x16x64_i8 v[124:127], v[108:111], v[194:197], v[124:127]
	v_mfma_i32_16x16x64_i8 v[116:119], v[120:123], v[194:197], v[116:119]
	v_mfma_i32_16x16x64_i8 v[92:95], v[108:111], v[202:205], v[92:95]
	v_mfma_i32_16x16x64_i8 v[88:91], v[120:123], v[202:205], v[88:91]
	v_mfma_i32_16x16x64_i8 v[76:79], v[108:111], v[210:213], v[76:79]
	v_mfma_i32_16x16x64_i8 v[72:75], v[120:123], v[210:213], v[72:75]
	v_mfma_i32_16x16x64_i8 v[132:135], v[158:161], v[182:185], v[132:135]
	v_mfma_i32_16x16x64_i8 v[128:131], v[174:177], v[182:185], v[128:131]
	v_mfma_i32_16x16x64_i8 v[100:103], v[158:161], v[190:193], v[100:103]
	v_mfma_i32_16x16x64_i8 v[96:99], v[174:177], v[190:193], v[96:99]
	v_mfma_i32_16x16x64_i8 v[84:87], v[158:161], v[198:201], v[84:87]
	v_mfma_i32_16x16x64_i8 v[80:83], v[174:177], v[198:201], v[80:83]
	v_mfma_i32_16x16x64_i8 v[68:71], v[158:161], v[206:209], v[68:71]
	v_mfma_i32_16x16x64_i8 v[64:67], v[174:177], v[206:209], v[64:67]
	v_mfma_i32_16x16x64_i8 v[132:135], v[170:173], v[186:189], v[132:135]
	v_mfma_i32_16x16x64_i8 v[128:131], v[178:181], v[186:189], v[128:131]
	v_mfma_i32_16x16x64_i8 v[100:103], v[170:173], v[194:197], v[100:103]
	v_mfma_i32_16x16x64_i8 v[96:99], v[178:181], v[194:197], v[96:99]
	v_mfma_i32_16x16x64_i8 v[84:87], v[170:173], v[202:205], v[84:87]
	v_mfma_i32_16x16x64_i8 v[80:83], v[178:181], v[202:205], v[80:83]
	v_mfma_i32_16x16x64_i8 v[68:71], v[170:173], v[210:213], v[68:71]
	v_mfma_i32_16x16x64_i8 v[64:67], v[178:181], v[210:213], v[64:67]
	s_barrier
	s_add_i32 s56, s48, s35
	v_lshl_add_u64 v[214:215], s[26:27], 0, v[146:147]
	s_mov_b32 m0, s56
	ds_read_b128 v[182:185], v169 offset:16384
	ds_read_b128 v[186:189], v169 offset:17408
	ds_read_b128 v[190:193], v169 offset:18432
	ds_read_b128 v[194:197], v169 offset:19456
	ds_read_b128 v[198:201], v169 offset:20480
	ds_read_b128 v[202:205], v169 offset:21504
	ds_read_b128 v[206:209], v169 offset:22528
	ds_read_b128 v[210:213], v169 offset:23552
	global_load_lds_dwordx4 v[214:215], off
	s_add_i32 m0, s56, 0x2000
	s_add_u32 s56, s26, 0x158000
	v_lshl_add_u64 v[216:217], s[26:27], 0, v[150:151]
	s_addc_u32 s57, s27, 0
	s_add_i32 s58, s49, s35
	global_load_lds_dwordx4 v[216:217], off
	v_lshl_add_u64 v[218:219], s[56:57], 0, v[146:147]
	s_mov_b32 m0, s58
	v_lshl_add_u64 v[220:221], s[28:29], 0, v[148:149]
	global_load_lds_dwordx4 v[218:219], off
	v_lshl_add_u64 v[218:219], s[56:57], 0, v[150:151]
	s_add_i32 m0, s58, 0x2000
	s_nop 0
	global_load_lds_dwordx4 v[218:219], off
	v_lshl_add_u64 v[218:219], s[28:29], 0, v[144:145]
	s_mov_b32 m0, s38
	s_nop 0
	global_load_lds_dwordx4 v[218:219], off
	s_mov_b32 m0, s39
	s_nop 0
	global_load_lds_dwordx4 v[220:221], off
	s_waitcnt vmcnt(8)
	s_waitcnt lgkmcnt(0)
	s_barrier
	s_waitcnt lgkmcnt(0)
	v_mfma_i32_16x16x64_i8 v[60:63], v[104:107], v[182:185], v[60:63]
	v_mfma_i32_16x16x64_i8 v[56:59], v[112:115], v[182:185], v[56:59]
	v_mfma_i32_16x16x64_i8 v[44:47], v[104:107], v[190:193], v[44:47]
	v_mfma_i32_16x16x64_i8 v[40:43], v[112:115], v[190:193], v[40:43]
	v_mfma_i32_16x16x64_i8 v[28:31], v[104:107], v[198:201], v[28:31]
	v_mfma_i32_16x16x64_i8 v[24:27], v[112:115], v[198:201], v[24:27]
	v_mfma_i32_16x16x64_i8 v[12:15], v[104:107], v[206:209], v[12:15]
	v_mfma_i32_16x16x64_i8 v[8:11], v[112:115], v[206:209], v[8:11]
	v_mfma_i32_16x16x64_i8 v[60:63], v[108:111], v[186:189], v[60:63]
	v_mfma_i32_16x16x64_i8 v[56:59], v[120:123], v[186:189], v[56:59]
	v_mfma_i32_16x16x64_i8 v[44:47], v[108:111], v[194:197], v[44:47]
	v_mfma_i32_16x16x64_i8 v[40:43], v[120:123], v[194:197], v[40:43]
	v_mfma_i32_16x16x64_i8 v[28:31], v[108:111], v[202:205], v[28:31]
	v_mfma_i32_16x16x64_i8 v[24:27], v[120:123], v[202:205], v[24:27]
	v_mfma_i32_16x16x64_i8 v[12:15], v[108:111], v[210:213], v[12:15]
	v_mfma_i32_16x16x64_i8 v[8:11], v[120:123], v[210:213], v[8:11]
	v_mfma_i32_16x16x64_i8 v[52:55], v[158:161], v[182:185], v[52:55]
	v_mfma_i32_16x16x64_i8 v[48:51], v[174:177], v[182:185], v[48:51]
	v_mfma_i32_16x16x64_i8 v[36:39], v[158:161], v[190:193], v[36:39]
	v_mfma_i32_16x16x64_i8 v[32:35], v[174:177], v[190:193], v[32:35]
	v_mfma_i32_16x16x64_i8 v[20:23], v[158:161], v[198:201], v[20:23]
	v_mfma_i32_16x16x64_i8 v[16:19], v[174:177], v[198:201], v[16:19]
	v_mfma_i32_16x16x64_i8 v[4:7], v[158:161], v[206:209], v[4:7]
	v_mfma_i32_16x16x64_i8 v[0:3], v[174:177], v[206:209], v[0:3]
	v_mfma_i32_16x16x64_i8 v[52:55], v[170:173], v[186:189], v[52:55]
	v_mfma_i32_16x16x64_i8 v[48:51], v[178:181], v[186:189], v[48:51]
	v_mfma_i32_16x16x64_i8 v[36:39], v[170:173], v[194:197], v[36:39]
	v_mfma_i32_16x16x64_i8 v[32:35], v[178:181], v[194:197], v[32:35]
	v_mfma_i32_16x16x64_i8 v[20:23], v[170:173], v[202:205], v[20:23]
	v_mfma_i32_16x16x64_i8 v[16:19], v[178:181], v[202:205], v[16:19]
	v_mfma_i32_16x16x64_i8 v[4:7], v[170:173], v[210:213], v[4:7]
	v_mfma_i32_16x16x64_i8 v[0:3], v[178:181], v[210:213], v[0:3]
	s_barrier
	s_add_i32 s56, 0, 0x18000
	s_add_i32 s57, 0, 0x1c000
	v_add_u32_e32 v120, s56, v165
	v_add_u32_e32 v162, s57, v165
	ds_read_b128 v[104:107], v120
	ds_read_b128 v[108:111], v120 offset:1024
	ds_read_b128 v[112:115], v120 offset:2048
	ds_read_b128 v[120:123], v120 offset:3072
	ds_read_b128 v[158:161], v162
	ds_read_b128 v[170:173], v162 offset:1024
	ds_read_b128 v[174:177], v162 offset:2048
	ds_read_b128 v[178:181], v162 offset:3072
	s_add_u32 s28, s28, 0x158000
	s_addc_u32 s29, s29, 0
	s_mov_b32 m0, s40
	v_lshl_add_u64 v[222:223], s[28:29], 0, v[144:145]
	ds_read_b128 v[182:185], v169 offset:32768
	ds_read_b128 v[186:189], v169 offset:33792
	ds_read_b128 v[190:193], v169 offset:34816
	ds_read_b128 v[194:197], v169 offset:35840
	ds_read_b128 v[198:201], v169 offset:36864
	ds_read_b128 v[202:205], v169 offset:37888
	ds_read_b128 v[206:209], v169 offset:38912
	ds_read_b128 v[210:213], v169 offset:39936
	global_load_lds_dwordx4 v[222:223], off
	v_lshl_add_u64 v[222:223], s[28:29], 0, v[148:149]
	s_mov_b32 m0, s41
	s_nop 0
	global_load_lds_dwordx4 v[222:223], off
	s_waitcnt vmcnt(8)
	s_waitcnt lgkmcnt(0)
	s_barrier
	s_waitcnt lgkmcnt(0)
	v_mfma_i32_16x16x64_i8 v[140:143], v[104:107], v[182:185], v[140:143]
	v_mfma_i32_16x16x64_i8 v[136:139], v[112:115], v[182:185], v[136:139]
	v_mfma_i32_16x16x64_i8 v[124:127], v[104:107], v[190:193], v[124:127]
	v_mfma_i32_16x16x64_i8 v[116:119], v[112:115], v[190:193], v[116:119]
	v_mfma_i32_16x16x64_i8 v[92:95], v[104:107], v[198:201], v[92:95]
	v_mfma_i32_16x16x64_i8 v[88:91], v[112:115], v[198:201], v[88:91]
	v_mfma_i32_16x16x64_i8 v[76:79], v[104:107], v[206:209], v[76:79]
	v_mfma_i32_16x16x64_i8 v[72:75], v[112:115], v[206:209], v[72:75]
	v_mfma_i32_16x16x64_i8 v[140:143], v[108:111], v[186:189], v[140:143]
	v_mfma_i32_16x16x64_i8 v[136:139], v[120:123], v[186:189], v[136:139]
	v_mfma_i32_16x16x64_i8 v[124:127], v[108:111], v[194:197], v[124:127]
	v_mfma_i32_16x16x64_i8 v[116:119], v[120:123], v[194:197], v[116:119]
	v_mfma_i32_16x16x64_i8 v[92:95], v[108:111], v[202:205], v[92:95]
	v_mfma_i32_16x16x64_i8 v[88:91], v[120:123], v[202:205], v[88:91]
	v_mfma_i32_16x16x64_i8 v[76:79], v[108:111], v[210:213], v[76:79]
	v_mfma_i32_16x16x64_i8 v[72:75], v[120:123], v[210:213], v[72:75]
	v_mfma_i32_16x16x64_i8 v[132:135], v[158:161], v[182:185], v[132:135]
	v_mfma_i32_16x16x64_i8 v[128:131], v[174:177], v[182:185], v[128:131]
	v_mfma_i32_16x16x64_i8 v[100:103], v[158:161], v[190:193], v[100:103]
	v_mfma_i32_16x16x64_i8 v[96:99], v[174:177], v[190:193], v[96:99]
	v_mfma_i32_16x16x64_i8 v[84:87], v[158:161], v[198:201], v[84:87]
	v_mfma_i32_16x16x64_i8 v[80:83], v[174:177], v[198:201], v[80:83]
	v_mfma_i32_16x16x64_i8 v[68:71], v[158:161], v[206:209], v[68:71]
	v_mfma_i32_16x16x64_i8 v[64:67], v[174:177], v[206:209], v[64:67]
	v_mfma_i32_16x16x64_i8 v[132:135], v[170:173], v[186:189], v[132:135]
	v_mfma_i32_16x16x64_i8 v[128:131], v[178:181], v[186:189], v[128:131]
	v_mfma_i32_16x16x64_i8 v[100:103], v[170:173], v[194:197], v[100:103]
	v_mfma_i32_16x16x64_i8 v[96:99], v[178:181], v[194:197], v[96:99]
	v_mfma_i32_16x16x64_i8 v[84:87], v[170:173], v[202:205], v[84:87]
	v_mfma_i32_16x16x64_i8 v[80:83], v[178:181], v[202:205], v[80:83]
	v_mfma_i32_16x16x64_i8 v[68:71], v[170:173], v[210:213], v[68:71]
	v_mfma_i32_16x16x64_i8 v[64:67], v[178:181], v[210:213], v[64:67]
	s_barrier
	s_add_i32 s28, s56, s35
	v_lshl_add_u64 v[214:215], v[214:215], 0, s[16:17]
	s_mov_b32 m0, s28
	ds_read_b128 v[182:185], v169 offset:49152
	ds_read_b128 v[186:189], v169 offset:50176
	ds_read_b128 v[190:193], v169 offset:51200
	ds_read_b128 v[194:197], v169 offset:52224
	ds_read_b128 v[198:201], v169 offset:53248
	ds_read_b128 v[202:205], v169 offset:54272
	ds_read_b128 v[206:209], v169 offset:55296
	ds_read_b128 v[210:213], v169 offset:56320
	global_load_lds_dwordx4 v[214:215], off
	s_add_i32 m0, s28, 0x2000
	s_add_u32 s26, s26, 0x158080
	v_lshl_add_u64 v[214:215], v[216:217], 0, s[16:17]
	s_addc_u32 s27, s27, 0
	s_add_i32 s28, s57, s35
	global_load_lds_dwordx4 v[214:215], off
	v_lshl_add_u64 v[214:215], s[26:27], 0, v[146:147]
	s_mov_b32 m0, s28
	s_nop 0
	global_load_lds_dwordx4 v[214:215], off
	v_lshl_add_u64 v[214:215], s[26:27], 0, v[150:151]
	s_add_i32 m0, s28, 0x2000
	s_nop 0
	global_load_lds_dwordx4 v[214:215], off
	v_lshl_add_u64 v[214:215], v[218:219], 0, s[16:17]
	s_mov_b32 m0, s42
	s_nop 0
	global_load_lds_dwordx4 v[214:215], off
	v_lshl_add_u64 v[214:215], v[220:221], 0, s[16:17]
	s_mov_b32 m0, s43
	s_nop 0
	global_load_lds_dwordx4 v[214:215], off
	s_waitcnt vmcnt(8)
	s_waitcnt lgkmcnt(0)
	s_barrier
	s_waitcnt lgkmcnt(0)
	v_mfma_i32_16x16x64_i8 v[60:63], v[104:107], v[182:185], v[60:63]
	v_mfma_i32_16x16x64_i8 v[56:59], v[112:115], v[182:185], v[56:59]
	v_mfma_i32_16x16x64_i8 v[44:47], v[104:107], v[190:193], v[44:47]
	v_mfma_i32_16x16x64_i8 v[40:43], v[112:115], v[190:193], v[40:43]
	v_mfma_i32_16x16x64_i8 v[28:31], v[104:107], v[198:201], v[28:31]
	v_mfma_i32_16x16x64_i8 v[24:27], v[112:115], v[198:201], v[24:27]
	v_mfma_i32_16x16x64_i8 v[12:15], v[104:107], v[206:209], v[12:15]
	v_mfma_i32_16x16x64_i8 v[8:11], v[112:115], v[206:209], v[8:11]
	v_mfma_i32_16x16x64_i8 v[60:63], v[108:111], v[186:189], v[60:63]
	v_mfma_i32_16x16x64_i8 v[56:59], v[120:123], v[186:189], v[56:59]
	v_mfma_i32_16x16x64_i8 v[44:47], v[108:111], v[194:197], v[44:47]
	v_mfma_i32_16x16x64_i8 v[40:43], v[120:123], v[194:197], v[40:43]
	v_mfma_i32_16x16x64_i8 v[28:31], v[108:111], v[202:205], v[28:31]
	v_mfma_i32_16x16x64_i8 v[24:27], v[120:123], v[202:205], v[24:27]
	v_mfma_i32_16x16x64_i8 v[12:15], v[108:111], v[210:213], v[12:15]
	v_mfma_i32_16x16x64_i8 v[8:11], v[120:123], v[210:213], v[8:11]
	v_mfma_i32_16x16x64_i8 v[52:55], v[158:161], v[182:185], v[52:55]
	v_mfma_i32_16x16x64_i8 v[48:51], v[174:177], v[182:185], v[48:51]
	v_mfma_i32_16x16x64_i8 v[36:39], v[158:161], v[190:193], v[36:39]
	v_mfma_i32_16x16x64_i8 v[32:35], v[174:177], v[190:193], v[32:35]
	v_mfma_i32_16x16x64_i8 v[20:23], v[158:161], v[198:201], v[20:23]
	v_mfma_i32_16x16x64_i8 v[16:19], v[174:177], v[198:201], v[16:19]
	v_mfma_i32_16x16x64_i8 v[4:7], v[158:161], v[206:209], v[4:7]
	v_mfma_i32_16x16x64_i8 v[0:3], v[174:177], v[206:209], v[0:3]
	v_mfma_i32_16x16x64_i8 v[52:55], v[170:173], v[186:189], v[52:55]
	v_mfma_i32_16x16x64_i8 v[48:51], v[178:181], v[186:189], v[48:51]
	v_mfma_i32_16x16x64_i8 v[36:39], v[170:173], v[194:197], v[36:39]
	v_mfma_i32_16x16x64_i8 v[32:35], v[178:181], v[194:197], v[32:35]
	v_mfma_i32_16x16x64_i8 v[20:23], v[170:173], v[202:205], v[20:23]
	v_mfma_i32_16x16x64_i8 v[16:19], v[178:181], v[202:205], v[16:19]
	v_mfma_i32_16x16x64_i8 v[4:7], v[170:173], v[210:213], v[4:7]
	v_mfma_i32_16x16x64_i8 v[0:3], v[178:181], v[210:213], v[0:3]
	s_barrier
	s_add_i32 s55, s55, 2
	s_add_u32 s6, s6, 0x100
	s_addc_u32 s7, s7, 0
	s_add_u32 s8, s8, 0x100
	s_addc_u32 s9, s9, 0
	s_cmpk_gt_u32 s55, 0x53
	s_cbranch_scc0 .LBB0_1166
	s_setprio 0
	s_and_b64 vcc, exec, s[18:19]
	s_cbranch_vccz .LBB0_1169
